# retention q loads batched; tail rowphase: split-K partial slab loads prefetched (8 round trips -> 2), gate/gpost and pre-norm vector loads hoisted
# speedup vs baseline: 1.0237x; 1.0001x over previous
; __device__ __forceinline__ float log_sigmoid(float x) { return -log1pf(expf(-x)); }
; __device__ __forceinline__ void m3_outputs(const KQ p_in, int e, bool ctx_full, unsigned char* smem, unsigned* scan_word) {
;     ...
;         if (!is_attn) {
;             const float lgf = log_sigmoid(dec[h]), lgb = log_sigmoid(dec[8 + h]);
;             __syncthreads();
.LBB0_960:
	v_add_u32_e32 v106, s7, v81
	s_bfe_u32 s6, s2, 0x30003
	s_mov_b64 s[0:1], -1
	s_andn2_b64 vcc, exec, s[36:37]
	v_ashrrev_i32_e32 v107, 31, v106
	v_lshlrev_b32_e32 v144, 1, v84
	s_cbranch_vccnz .LBB0_962
	s_lshl_b32 s0, s6, 2
	s_add_u32 s0, s73, s0
	s_addc_u32 s1, s64, 0
	v_mov_b64_e32 v[0:1], s[0:1]
	global_load_dword v2, v[0:1], off
	s_mov_b32 s0, 0xc2b17218
	global_load_dword v0, v[0:1], off offset:32
	s_mov_b32 s11, 0x3f2aaaab
	s_mov_b32 s12, 0x3f317218
	s_mov_b32 s1, 0x7f800000
	s_mov_b32 s10, 0x33800000
	s_lshl_b32 s80, s6, 7
	s_waitcnt lgkmcnt(0)
	s_barrier
	s_waitcnt vmcnt(2)
	s_waitcnt vmcnt(1)
	v_mul_f32_e32 v3, 0xbfb8aa3b, v2
	v_fma_f32 v4, v2, s42, -v3
	v_rndne_f32_e32 v5, v3
	v_fmac_f32_e32 v4, 0xb2a5705f, v2
	v_sub_f32_e32 v3, v3, v5
	v_add_f32_e32 v3, v3, v4
	v_exp_f32_e32 v3, v3
	v_cvt_i32_f32_e32 v4, v5
	v_cmp_nlt_f32_e32 vcc, s9, v2
	s_waitcnt vmcnt(0)
	v_mul_f32_e32 v1, 0xbfb8aa3b, v0
	v_ldexp_f32 v3, v3, v4
	v_cndmask_b32_e32 v3, 0, v3, vcc
	v_cmp_ngt_f32_e32 vcc, s0, v2
	s_nop 1
	v_cndmask_b32_e32 v16, v203, v3, vcc
	v_add_f32_e32 v4, 1.0, v16
	v_add_f32_e32 v2, -1.0, v4
	v_sub_f32_e32 v3, v2, v4
	v_add_f32_e32 v3, 1.0, v3
	v_sub_f32_e32 v2, v16, v2
	v_add_f32_e32 v5, v2, v3
	v_frexp_mant_f32_e32 v2, v4
	v_cmp_gt_f32_e32 vcc, s11, v2
	v_cvt_f64_f32_e32 v[2:3], v4
	v_frexp_exp_i32_f64_e32 v2, v[2:3]
	v_subbrev_co_u32_e32 v10, vcc, 0, v2, vcc
	v_sub_u32_e32 v2, 0, v10
	v_ldexp_f32 v3, v4, v2
	v_add_f32_e32 v4, -1.0, v3
	v_add_f32_e32 v6, 1.0, v3
	v_ldexp_f32 v2, v5, v2
	v_add_f32_e32 v5, 1.0, v4
	v_add_f32_e32 v7, -1.0, v6
	v_sub_f32_e32 v5, v3, v5
	v_sub_f32_e32 v3, v3, v7
	v_add_f32_e32 v5, v2, v5
	v_add_f32_e32 v2, v2, v3
	v_add_f32_e32 v11, v6, v2
	v_rcp_f32_e32 v13, v11
	v_sub_f32_e32 v3, v6, v11
	v_add_f32_e32 v12, v2, v3
	v_add_f32_e32 v3, v4, v5
	v_mul_f32_e32 v15, v3, v13
	v_sub_f32_e32 v2, v4, v3
	v_mul_f32_e32 v4, v11, v15
	v_fma_f32 v6, v15, v11, -v4
	v_fmac_f32_e32 v6, v15, v12
	v_add_f32_e32 v14, v5, v2
	v_add_f32_e32 v2, v4, v6
	v_sub_f32_e32 v5, v3, v2
	v_pk_add_f32 v[8:9], v[2:3], v[4:5] neg_lo:[0,1] neg_hi:[0,1]
	v_mov_b32_e32 v7, v2
	v_pk_add_f32 v[2:3], v[8:9], v[6:7] neg_lo:[0,1] neg_hi:[0,1]
	v_cmp_neq_f32_e32 vcc, s1, v16
	v_add_f32_e32 v3, v14, v3
	v_add_f32_e32 v2, v2, v3
	v_add_f32_e32 v3, v5, v2
	v_mul_f32_e32 v14, v13, v3
	v_mul_f32_e32 v4, v11, v14
	v_fma_f32 v6, v14, v11, -v4
	v_fmac_f32_e32 v6, v14, v12
	v_sub_f32_e32 v5, v5, v3
	v_add_f32_e32 v11, v2, v5
	v_add_f32_e32 v2, v4, v6
	v_sub_f32_e32 v5, v3, v2
	v_pk_add_f32 v[8:9], v[2:3], v[4:5] neg_lo:[0,1] neg_hi:[0,1]
	v_mov_b32_e32 v7, v2
	v_pk_add_f32 v[2:3], v[8:9], v[6:7] neg_lo:[0,1] neg_hi:[0,1]
	s_nop 0
	v_add_f32_e32 v3, v11, v3
	v_add_f32_e32 v2, v2, v3
	v_add_f32_e32 v3, v15, v14
	v_add_f32_e32 v2, v5, v2
	v_sub_f32_e32 v4, v3, v15
	v_mul_f32_e32 v2, v13, v2
	v_sub_f32_e32 v4, v14, v4
	v_add_f32_e32 v4, v4, v2
	v_add_f32_e32 v6, v3, v4
	v_mul_f32_e32 v7, v6, v6
	v_fmamk_f32 v2, v7, 0x3e9b6dac, v191
	v_fmaak_f32 v149, v7, v2, 0x3f2aaada
	v_cvt_f32_i32_e32 v2, v10
	v_sub_f32_e32 v3, v6, v3
	v_sub_f32_e32 v3, v4, v3
	v_ldexp_f32 v8, v3, 1
	v_mul_f32_e32 v3, v6, v7
	v_ldexp_f32 v5, v6, 1
	v_pk_mul_f32 v[6:7], v[2:3], v[148:149]
	s_nop 0
	v_fma_f32 v4, v2, s12, -v6
	v_fmac_f32_e32 v4, 0xb102e308, v2
	v_pk_add_f32 v[2:3], v[6:7], v[4:5]
	s_nop 0
	v_sub_f32_e32 v5, v3, v5
	v_sub_f32_e32 v5, v7, v5
	v_add_f32_e32 v9, v8, v5
	v_mov_b32_e32 v8, v6
	v_pk_add_f32 v[6:7], v[2:3], v[6:7] neg_lo:[0,1] neg_hi:[0,1]
	v_pk_add_f32 v[10:11], v[2:3], v[8:9]
	v_mov_b32_e32 v5, v2
	v_mov_b32_e32 v7, v11
	v_pk_add_f32 v[12:13], v[4:5], v[6:7] neg_lo:[0,1] neg_hi:[0,1]
	v_pk_add_f32 v[4:5], v[4:5], v[6:7]
	v_mov_b32_e32 v8, v9
	v_pk_add_f32 v[6:7], v[4:5], v[2:3] op_sel:[1,0] op_sel_hi:[0,1] neg_lo:[0,1] neg_hi:[0,1]
	v_pk_add_f32 v[14:15], v[10:11], v[6:7] op_sel_hi:[1,0] neg_lo:[0,1] neg_hi:[0,1]
	v_mov_b32_e32 v10, v11
	v_mov_b32_e32 v11, v5
	v_pk_mov_b32 v[6:7], v[2:3], v[6:7] op_sel:[1,0]
	v_mov_b32_e32 v9, v2
	v_pk_add_f32 v[6:7], v[10:11], v[6:7] neg_lo:[0,1] neg_hi:[0,1]
	v_mov_b32_e32 v14, v12
	v_pk_add_f32 v[2:3], v[8:9], v[6:7] neg_lo:[0,1] neg_hi:[0,1]
	v_mov_b32_e32 v13, v5
	v_pk_add_f32 v[6:7], v[14:15], v[2:3]
	s_nop 0
	v_pk_add_f32 v[8:9], v[6:7], v[6:7] op_sel:[0,1] op_sel_hi:[1,0]
	s_nop 0
	v_pk_add_f32 v[4:5], v[4:5], v[8:9] op_sel:[1,0] op_sel_hi:[0,1]
	v_mov_b32_e32 v7, v4
	v_pk_add_f32 v[10:11], v[6:7], v[12:13] neg_lo:[0,1] neg_hi:[0,1]
	v_mov_b32_e32 v3, v8
	v_sub_f32_e32 v5, v6, v10
	v_pk_add_f32 v[2:3], v[2:3], v[10:11] neg_lo:[0,1] neg_hi:[0,1]
	v_sub_f32_e32 v5, v12, v5
	v_add_f32_e32 v2, v2, v5
	v_add_f32_e32 v2, v2, v3
	v_add_f32_e32 v2, v4, v2
	v_cndmask_b32_e32 v2, v203, v2, vcc
	v_cmp_lt_f32_e64 vcc, |v16|, s10
	v_rndne_f32_e32 v3, v1
	s_nop 0
	v_cndmask_b32_e32 v26, v2, v16, vcc
	v_fma_f32 v2, v0, s42, -v1
	v_fmac_f32_e32 v2, 0xb2a5705f, v0
	v_sub_f32_e32 v1, v1, v3
	v_add_f32_e32 v1, v1, v2
	v_exp_f32_e32 v1, v1
	v_cvt_i32_f32_e32 v2, v3
	v_cmp_nlt_f32_e32 vcc, s9, v0
	v_ldexp_f32 v1, v1, v2
	s_nop 0
	v_cndmask_b32_e32 v1, 0, v1, vcc
	v_cmp_ngt_f32_e32 vcc, s0, v0
	s_nop 1
	v_cndmask_b32_e32 v14, v203, v1, vcc
	v_add_f32_e32 v2, 1.0, v14
	v_add_f32_e32 v0, -1.0, v2
	v_sub_f32_e32 v1, v0, v2
	v_add_f32_e32 v1, 1.0, v1
	v_sub_f32_e32 v0, v14, v0
	v_add_f32_e32 v3, v0, v1
	v_frexp_mant_f32_e32 v0, v2
	v_cmp_gt_f32_e32 vcc, s11, v0
	v_cvt_f64_f32_e32 v[0:1], v2
	v_frexp_exp_i32_f64_e32 v0, v[0:1]
	v_subbrev_co_u32_e32 v8, vcc, 0, v0, vcc
	v_sub_u32_e32 v0, 0, v8
	v_ldexp_f32 v1, v2, v0
	v_add_f32_e32 v2, -1.0, v1
	v_add_f32_e32 v4, 1.0, v1
	v_ldexp_f32 v0, v3, v0
	v_add_f32_e32 v3, 1.0, v2
	v_add_f32_e32 v5, -1.0, v4
; __device__ __forceinline__ float log_sigmoid(float x) { return -log1pf(expf(-x)); }
; __device__ __forceinline__ void m3_outputs(const KQ p_in, int e, bool ctx_full, unsigned char* smem, unsigned* scan_word) {
;     ...
;             for (int q = 0; q < 2; ++q) { const int idx = tid + 512 * q; const int r = idx >> 3, pc = idx & 7; const bf16_t* zr = Z + (size_t)(t0 + r) * INW + h * 64 + pc * 8;
;                 *(u32x4*)(Kt + r * 72 + pc * 8) = *(const u32x4*)(zr + 1792);
;                 const bf16x8 vv = *(const bf16x8*)(zr + 2304);
; #pragma unroll
;                 for (int j = 0; j < 8; ++j) Vt[(pc * 8 + j) * 136 + (r ^ (pc << 2))] = (bf16_t)vv[j]; }
;             const size_t so = ((size_t)(b * NCH + cidx) * 8 + h) * 4096;
;             {
;                 const int ee = tid & 63, d0 = (tid >> 6) * 8;
;                 float tf[8], tb[8];
; #pragma unroll
;                 for (int j = 0; j < 8; ++j) { tf[j] = TF[so + (d0 + j) * 64 + ee]; tb[j] = TB[so + (d0 + j) * 64 + ee]; }
	v_sub_f32_e32 v3, v1, v3
	v_sub_f32_e32 v1, v1, v5
	v_add_f32_e32 v3, v0, v3
	v_add_f32_e32 v0, v0, v1
	v_add_f32_e32 v9, v4, v0
	v_rcp_f32_e32 v11, v9
	v_sub_f32_e32 v1, v4, v9
	v_add_f32_e32 v10, v0, v1
	v_add_f32_e32 v1, v2, v3
	v_mul_f32_e32 v13, v1, v11
	v_sub_f32_e32 v0, v2, v1
	v_mul_f32_e32 v2, v9, v13
	v_fma_f32 v4, v13, v9, -v2
	v_fmac_f32_e32 v4, v13, v10
	v_add_f32_e32 v12, v3, v0
	v_add_f32_e32 v0, v2, v4
	v_sub_f32_e32 v3, v1, v0
	v_pk_add_f32 v[6:7], v[0:1], v[2:3] neg_lo:[0,1] neg_hi:[0,1]
	v_mov_b32_e32 v5, v0
	v_pk_add_f32 v[0:1], v[6:7], v[4:5] neg_lo:[0,1] neg_hi:[0,1]
	v_cmp_neq_f32_e32 vcc, s1, v14
	v_add_f32_e32 v1, v12, v1
	v_add_f32_e32 v0, v0, v1
	v_add_f32_e32 v1, v3, v0
	v_mul_f32_e32 v12, v11, v1
	v_mul_f32_e32 v2, v9, v12
	v_fma_f32 v4, v12, v9, -v2
	v_fmac_f32_e32 v4, v12, v10
	v_sub_f32_e32 v3, v3, v1
	v_add_f32_e32 v9, v0, v3
	v_add_f32_e32 v0, v2, v4
	v_sub_f32_e32 v3, v1, v0
	v_pk_add_f32 v[6:7], v[0:1], v[2:3] neg_lo:[0,1] neg_hi:[0,1]
	v_mov_b32_e32 v5, v0
	v_pk_add_f32 v[0:1], v[6:7], v[4:5] neg_lo:[0,1] neg_hi:[0,1]
	s_nop 0
	v_add_f32_e32 v1, v9, v1
	v_add_f32_e32 v0, v0, v1
	v_add_f32_e32 v1, v13, v12
	v_add_f32_e32 v0, v3, v0
	v_sub_f32_e32 v2, v1, v13
	v_mul_f32_e32 v0, v11, v0
	v_sub_f32_e32 v2, v12, v2
	v_add_f32_e32 v2, v2, v0
	v_add_f32_e32 v4, v1, v2
	v_mul_f32_e32 v5, v4, v4
	v_fmamk_f32 v0, v5, 0x3e9b6dac, v191
	v_fmaak_f32 v149, v5, v0, 0x3f2aaada
	v_cvt_f32_i32_e32 v0, v8
	v_sub_f32_e32 v1, v4, v1
	v_sub_f32_e32 v1, v2, v1
	v_ldexp_f32 v6, v1, 1
	v_mul_f32_e32 v1, v4, v5
	v_ldexp_f32 v3, v4, 1
	v_pk_mul_f32 v[4:5], v[0:1], v[148:149]
	s_nop 0
	v_fma_f32 v2, v0, s12, -v4
	v_fmac_f32_e32 v2, 0xb102e308, v0
	v_pk_add_f32 v[0:1], v[4:5], v[2:3]
	s_nop 0
	v_sub_f32_e32 v3, v1, v3
	v_sub_f32_e32 v3, v5, v3
	v_add_f32_e32 v7, v6, v3
	v_mov_b32_e32 v6, v4
	v_pk_add_f32 v[4:5], v[0:1], v[4:5] neg_lo:[0,1] neg_hi:[0,1]
	v_pk_add_f32 v[8:9], v[0:1], v[6:7]
	v_mov_b32_e32 v3, v0
	v_mov_b32_e32 v5, v9
	v_pk_add_f32 v[10:11], v[2:3], v[4:5] neg_lo:[0,1] neg_hi:[0,1]
	v_pk_add_f32 v[2:3], v[2:3], v[4:5]
	v_mov_b32_e32 v6, v7
	v_pk_add_f32 v[4:5], v[2:3], v[0:1] op_sel:[1,0] op_sel_hi:[0,1] neg_lo:[0,1] neg_hi:[0,1]
	v_pk_add_f32 v[12:13], v[8:9], v[4:5] op_sel_hi:[1,0] neg_lo:[0,1] neg_hi:[0,1]
	v_mov_b32_e32 v8, v9
	v_mov_b32_e32 v9, v3
	v_pk_mov_b32 v[4:5], v[0:1], v[4:5] op_sel:[1,0]
	v_mov_b32_e32 v7, v0
	v_pk_add_f32 v[4:5], v[8:9], v[4:5] neg_lo:[0,1] neg_hi:[0,1]
	v_mov_b32_e32 v12, v10
	v_pk_add_f32 v[0:1], v[6:7], v[4:5] neg_lo:[0,1] neg_hi:[0,1]
	v_mov_b32_e32 v11, v3
	v_pk_add_f32 v[4:5], v[12:13], v[0:1]
	s_nop 0
	v_pk_add_f32 v[6:7], v[4:5], v[4:5] op_sel:[0,1] op_sel_hi:[1,0]
	s_nop 0
	v_pk_add_f32 v[2:3], v[2:3], v[6:7] op_sel:[1,0] op_sel_hi:[0,1]
	v_mov_b32_e32 v5, v2
	v_pk_add_f32 v[8:9], v[4:5], v[10:11] neg_lo:[0,1] neg_hi:[0,1]
	v_mov_b32_e32 v1, v6
	v_sub_f32_e32 v3, v4, v8
	v_pk_add_f32 v[0:1], v[0:1], v[8:9] neg_lo:[0,1] neg_hi:[0,1]
	v_sub_f32_e32 v3, v10, v3
	v_add_f32_e32 v0, v0, v3
	v_add_f32_e32 v0, v0, v1
	v_add_f32_e32 v0, v2, v0
	v_cndmask_b32_e32 v0, v203, v0, vcc
	v_cmp_lt_f32_e64 vcc, |v14|, s10
	v_add_u32_e32 v2, s7, v114
	s_nop 0
	v_cndmask_b32_e32 v27, v0, v14, vcc
	v_lshl_add_u64 v[0:1], v[82:83], 0, s[80:81]
	v_mad_i64_i32 v[6:7], s[0:1], v2, s54, v[0:1]
	global_load_dwordx4 v[64:67], v[6:7], off offset:3584
	v_add_co_u32_e32 v2, vcc, s43, v6
	s_nop 1
	v_addc_co_u32_e32 v3, vcc, 0, v7, vcc
	global_load_dwordx4 v[68:71], v[2:3], off offset:512
	v_add_u32_e32 v2, s7, v115
	v_mad_i64_i32 v[4:5], s[0:1], v2, s54, v[0:1]
	global_load_dwordx4 v[72:75], v[4:5], off offset:3584
	v_add_co_u32_e32 v0, vcc, s43, v4
	s_nop 1
	v_addc_co_u32_e32 v1, vcc, 0, v5, vcc
	global_load_dwordx4 v[76:79], v[0:1], off offset:512
	s_mul_i32 s0, s5, 34
	s_add_i32 s0, s0, s8
	s_ashr_i32 s1, s0, 31
	s_lshl_b64 s[0:1], s[0:1], 15
	s_lshl_b32 s7, s6, 12
	s_or_b32 s0, s0, s7
	v_mov_b32_e32 v3, s1
	v_or_b32_e32 v2, s0, v80
	v_lshl_add_u64 v[0:1], v[2:3], 0, v[90:91]
	v_lshl_add_u64 v[6:7], v[2:3], 0, v[92:93]
	v_lshl_add_u64 v[10:11], v[2:3], 0, v[94:95]
	v_lshl_add_u64 v[14:15], v[2:3], 0, v[96:97]
	v_lshl_add_u64 v[18:19], v[2:3], 0, v[98:99]
	v_lshlrev_b64 v[0:1], 2, v[0:1]
	v_lshlrev_b64 v[6:7], 2, v[6:7]
	v_lshlrev_b64 v[10:11], 2, v[10:11]
	v_lshlrev_b64 v[14:15], 2, v[14:15]
	v_lshlrev_b64 v[18:19], 2, v[18:19]
	v_lshl_add_u64 v[22:23], v[2:3], 0, v[100:101]
	v_lshl_add_u64 v[28:29], v[2:3], 0, v[102:103]
	v_lshl_add_u64 v[2:3], v[2:3], 0, v[104:105]
	v_lshl_add_u64 v[4:5], s[92:93], 0, v[0:1]
	v_lshl_add_u64 v[8:9], s[92:93], 0, v[6:7]
	v_lshl_add_u64 v[6:7], s[94:95], 0, v[6:7]
	v_lshl_add_u64 v[12:13], s[92:93], 0, v[10:11]
	v_lshl_add_u64 v[10:11], s[94:95], 0, v[10:11]
	v_lshl_add_u64 v[16:17], s[92:93], 0, v[14:15]
	v_lshl_add_u64 v[14:15], s[94:95], 0, v[14:15]
	v_lshl_add_u64 v[20:21], s[92:93], 0, v[18:19]
	v_lshl_add_u64 v[18:19], s[94:95], 0, v[18:19]
	v_lshlrev_b64 v[22:23], 2, v[22:23]
	v_lshlrev_b64 v[28:29], 2, v[28:29]
	v_lshlrev_b64 v[2:3], 2, v[2:3]
	v_lshl_add_u64 v[0:1], s[94:95], 0, v[0:1]
	v_lshl_add_u64 v[24:25], s[92:93], 0, v[22:23]
	v_lshl_add_u64 v[22:23], s[94:95], 0, v[22:23]
	v_lshl_add_u64 v[30:31], s[92:93], 0, v[28:29]
	v_lshl_add_u64 v[28:29], s[94:95], 0, v[28:29]
	v_lshl_add_u64 v[32:33], s[92:93], 0, v[2:3]
	v_lshl_add_u64 v[2:3], s[94:95], 0, v[2:3]
	global_load_dword v8, v[8:9], off
	s_nop 0
	global_load_dword v4, v[4:5], off
	s_nop 0
	global_load_dword v5, v[16:17], off
	global_load_dword v9, v[12:13], off
	s_nop 0
	global_load_dword v12, v[24:25], off
	global_load_dword v13, v[20:21], off
	global_load_dword v16, v[32:33], off
	global_load_dword v17, v[30:31], off
	s_nop 0
	global_load_dword v6, v[6:7], off
	s_nop 0
	global_load_dword v7, v[0:1], off
	s_nop 0
	global_load_dword v14, v[14:15], off
	s_nop 0
	global_load_dword v10, v[10:11], off
	s_nop 0
	global_load_dword v11, v[22:23], off
	global_load_dword v15, v[18:19], off
	s_nop 0
	global_load_dword v18, v[2:3], off
	global_load_dword v19, v[28:29], off
	s_waitcnt lgkmcnt(0)
; __device__ __forceinline__ float bf2f(bf16_t b) { return __uint_as_float(((unsigned)b) << 16); }
; __device__ __forceinline__ void m3_outputs(const KQ p_in, int e, bool ctx_full, unsigned char* smem, unsigned* scan_word) {
;     ...
;                 *(u32x4*)(TfT + ee * 72 + d0) = wf4; *(u32x4*)(TbT + ee * 72 + d0) = wb4;
;             }
;             __builtin_amdgcn_sched_barrier(0);
;             bf16x8 qf[2], qff[2], qfb[2];
;             { const bf16_t* qr = Z + (size_t)(t0 + i) * INW + 512 + h * 64 + 8 * g4;
;               const float cf = __expf(lgf * (float)(i + 1)), cb = __expf(lgb * (float)(128 - i));
; #pragma unroll
;               for (int k2 = 0; k2 < 2; ++k2) { qf[k2] = *(const bf16x8*)(qr + 32 * k2);
;                   f32x4 a0, a1, b0, b1;
; #pragma unroll
;                   for (int j = 0; j < 4; ++j) { const float x0 = bf2f((bf16_t)qf[k2][j]), x1 = bf2f((bf16_t)qf[k2][4 + j]); a0[j] = x0 * cf; a1[j] = x1 * cf; b0[j] = x0 * cb; b1[j] = x1 * cb; }
;                   qff[k2] = pack8(a0, a1); qfb[k2] = pack8(b0, b1); } }
;             __builtin_amdgcn_sched_barrier(0);
;             __syncthreads();
; #pragma unroll
;             for (int m = 0; m < 4; ++m)
; #pragma unroll
;                 for (int k2 = 0; k2 < 2; ++k2) {
;                     const bf16x8 af = *(const bf16x8*)(TfT + (16 * m + ln) * 72 + 32 * k2 + 8 * g4);
;                     const bf16x8 ab = *(const bf16x8*)(TbT + (16 * m + ln) * 72 + 32 * k2 + 8 * g4);
;                     O[m] = __builtin_amdgcn_mfma_f32_16x16x32_bf16(af, qff[k2], O[m], 0, 0, 0);
;                     O[m] = __builtin_amdgcn_mfma_f32_16x16x32_bf16(ab, qfb[k2], O[m], 0, 0, 0);
	s_waitcnt vmcnt(19) lgkmcnt(0)
	ds_write_b128 v158, v[64:67]
	s_waitcnt vmcnt(18)
	ds_write_b16 v159, v68 offset:18432
	ds_write_b16_d16_hi v159, v68 offset:18704
	ds_write_b16 v159, v69 offset:18976
	ds_write_b16_d16_hi v159, v69 offset:19248
	ds_write_b16 v159, v70 offset:19520
	ds_write_b16_d16_hi v159, v70 offset:19792
	ds_write_b16 v159, v71 offset:20064
	ds_write_b16_d16_hi v159, v71 offset:20336
	s_waitcnt vmcnt(17)
	ds_write_b128 v160, v[72:75]
	s_waitcnt vmcnt(16)
	ds_write_b16 v161, v76 offset:18432
	ds_write_b16_d16_hi v161, v76 offset:18704
	ds_write_b16 v161, v77 offset:18976
	ds_write_b16_d16_hi v161, v77 offset:19248
	ds_write_b16 v161, v78 offset:19520
	ds_write_b16_d16_hi v161, v78 offset:19792
	ds_write_b16 v161, v79 offset:20064
	ds_write_b16_d16_hi v161, v79 offset:20336
	s_waitcnt vmcnt(14)
	v_cvt_pk_bf16_f32 v0, v4, v8
	s_waitcnt vmcnt(12)
	v_cvt_pk_bf16_f32 v1, v9, v5
	s_waitcnt vmcnt(10)
	v_cvt_pk_bf16_f32 v2, v13, v12
	s_waitcnt vmcnt(8)
	v_cvt_pk_bf16_f32 v3, v17, v16
	s_waitcnt vmcnt(6)
	v_cvt_pk_bf16_f32 v4, v7, v6
	s_waitcnt vmcnt(4)
	v_cvt_pk_bf16_f32 v5, v10, v14
	s_waitcnt vmcnt(2)
	v_cvt_pk_bf16_f32 v6, v15, v11
	s_waitcnt vmcnt(0)
	v_cvt_pk_bf16_f32 v7, v19, v18
	ds_write_b128 v85, v[0:3] offset:35840
	ds_write_b128 v85, v[4:7] offset:45056
	v_mov_b64_e32 v[0:1], s[88:89]
	v_mad_i64_i32 v[0:1], s[0:1], v106, s54, v[0:1]
	v_lshl_add_u64 v[24:25], v[0:1], 0, s[80:81]
	v_lshl_add_u64 v[4:5], v[24:25], 0, v[144:145]
	global_load_dwordx4 v[0:3], v[4:5], off offset:1024
	global_load_dwordx4 v[64:67], v[4:5], off offset:1088
	v_mul_f32_e32 v6, v87, v26
	v_mul_f32_e32 v7, v110, v27
	v_mul_f32_e32 v6, 0xbfb8aa3b, v6
	v_mul_f32_e32 v7, 0xbfb8aa3b, v7
	v_exp_f32_e32 v6, v6
	v_exp_f32_e32 v7, v7
	s_waitcnt lgkmcnt(0)
	s_waitcnt vmcnt(1)
	v_lshlrev_b32_e32 v8, 16, v0
	v_lshlrev_b32_e32 v9, 16, v2
	v_and_b32_e32 v10, 0xffff0000, v0
	v_and_b32_e32 v11, 0xffff0000, v2
	v_lshlrev_b32_e32 v12, 16, v1
	v_lshlrev_b32_e32 v13, 16, v3
	v_and_b32_e32 v14, 0xffff0000, v1
	v_and_b32_e32 v15, 0xffff0000, v3
	v_mul_f32_e32 v16, v6, v8
	v_mul_f32_e32 v18, v6, v9
	v_mul_f32_e32 v17, v6, v10
	v_mul_f32_e32 v19, v6, v11
	v_mul_f32_e32 v20, v6, v12
	v_mul_f32_e32 v21, v6, v13
	v_mul_f32_e32 v22, v6, v14
	v_mul_f32_e32 v23, v6, v15
	v_mul_f32_e32 v8, v7, v8
	v_mul_f32_e32 v9, v7, v9
	v_mul_f32_e32 v10, v7, v10
	v_mul_f32_e32 v11, v7, v11
	v_mul_f32_e32 v12, v7, v12
	v_mul_f32_e32 v13, v7, v13
	v_mul_f32_e32 v14, v7, v14
	v_mul_f32_e32 v15, v7, v15
	v_cvt_pk_bf16_f32 v16, v16, v17
	v_cvt_pk_bf16_f32 v17, v20, v22
	v_cvt_pk_bf16_f32 v18, v18, v19
	v_cvt_pk_bf16_f32 v19, v21, v23
	v_cvt_pk_bf16_f32 v28, v8, v10
	v_cvt_pk_bf16_f32 v29, v12, v14
	v_cvt_pk_bf16_f32 v30, v9, v11
	v_cvt_pk_bf16_f32 v31, v13, v15
	s_waitcnt vmcnt(0)
	v_mov_b32_e32 v20, v64
	v_mov_b32_e32 v21, v65
	v_mov_b32_e32 v22, v66
	v_mov_b32_e32 v23, v67
	s_waitcnt lgkmcnt(0)
	s_waitcnt vmcnt(0)
	v_and_b32_e32 v8, 0xffff0000, v64
	v_and_b32_e32 v9, 0xffff0000, v66
	v_lshlrev_b32_e32 v10, 16, v65
	v_lshlrev_b32_e32 v11, 16, v67
	v_and_b32_e32 v12, 0xffff0000, v65
	v_lshlrev_b32_e32 v4, 16, v64
	v_lshlrev_b32_e32 v5, 16, v66
	v_and_b32_e32 v13, 0xffff0000, v67
	v_mul_f32_e32 v32, v6, v8
	v_mul_f32_e32 v34, v6, v9
	v_mul_f32_e32 v33, v6, v10
	v_mul_f32_e32 v35, v6, v11
	v_mul_f32_e32 v36, v6, v12
	v_mul_f32_e32 v14, v6, v4
	v_mul_f32_e32 v15, v6, v5
	v_mul_f32_e32 v4, v7, v4
	v_mul_f32_e32 v5, v7, v5
	v_mul_f32_e32 v8, v7, v8
	v_mul_f32_e32 v9, v7, v9
	v_mul_f32_e32 v10, v7, v10
	v_mul_f32_e32 v11, v7, v11
	v_mul_f32_e32 v6, v6, v13
	v_mul_f32_e32 v12, v7, v12
	v_mul_f32_e32 v7, v7, v13
	v_cvt_pk_bf16_f32 v32, v14, v32
	v_cvt_pk_bf16_f32 v33, v33, v36
	v_cvt_pk_bf16_f32 v34, v15, v34
	v_cvt_pk_bf16_f32 v35, v35, v6
	v_cvt_pk_bf16_f32 v36, v4, v8
	v_cvt_pk_bf16_f32 v37, v10, v12
	v_cvt_pk_bf16_f32 v38, v5, v9
	v_cvt_pk_bf16_f32 v39, v11, v7
	s_barrier
	ds_read_b128 v[4:7], v116 offset:35840
	ds_read_b128 v[8:11], v116 offset:45056
	s_waitcnt lgkmcnt(1)
	v_mfma_f32_16x16x32_bf16 v[4:7], v[4:7], v[16:19], 0
	s_waitcnt lgkmcnt(0)
	v_mfma_f32_16x16x32_bf16 v[4:7], v[8:11], v[28:31], v[4:7]
	ds_read_b128 v[8:11], v116 offset:35904
	s_waitcnt lgkmcnt(0)
	v_mfma_f32_16x16x32_bf16 v[4:7], v[8:11], v[32:35], v[4:7]
	ds_read_b128 v[8:11], v116 offset:45120
	s_waitcnt lgkmcnt(0)
	v_mfma_f32_16x16x32_bf16 v[4:7], v[8:11], v[36:39], v[4:7]
	ds_read_b128 v[8:11], v116 offset:38144
	ds_read_b128 v[12:15], v116 offset:47360
	s_waitcnt lgkmcnt(1)
	v_mfma_f32_16x16x32_bf16 v[8:11], v[8:11], v[16:19], 0
	s_waitcnt lgkmcnt(0)
	v_mfma_f32_16x16x32_bf16 v[8:11], v[12:15], v[28:31], v[8:11]
	ds_read_b128 v[12:15], v116 offset:38208
	s_waitcnt lgkmcnt(0)
	v_mfma_f32_16x16x32_bf16 v[8:11], v[12:15], v[32:35], v[8:11]
	ds_read_b128 v[12:15], v116 offset:47424
	s_waitcnt lgkmcnt(0)
	v_mfma_f32_16x16x32_bf16 v[8:11], v[12:15], v[36:39], v[8:11]
	ds_read_b128 v[12:15], v116 offset:40448
	ds_read_b128 v[40:43], v116 offset:49664
	s_waitcnt lgkmcnt(1)
	v_mfma_f32_16x16x32_bf16 v[12:15], v[12:15], v[16:19], 0
	s_waitcnt lgkmcnt(0)
	v_mfma_f32_16x16x32_bf16 v[12:15], v[40:43], v[28:31], v[12:15]
	ds_read_b128 v[40:43], v116 offset:40512
	s_waitcnt lgkmcnt(0)
	v_mfma_f32_16x16x32_bf16 v[12:15], v[40:43], v[32:35], v[12:15]
	ds_read_b128 v[40:43], v116 offset:49728
	s_waitcnt lgkmcnt(0)
	v_mfma_f32_16x16x32_bf16 v[12:15], v[40:43], v[36:39], v[12:15]
	ds_read_b128 v[40:43], v116 offset:42752
	s_waitcnt lgkmcnt(0)
	v_mfma_f32_16x16x32_bf16 v[16:19], v[40:43], v[16:19], 0
	ds_read_b128 v[40:43], v116 offset:51968
	s_waitcnt lgkmcnt(0)
	v_mfma_f32_16x16x32_bf16 v[16:19], v[40:43], v[28:31], v[16:19]
	ds_read_b128 v[28:31], v116 offset:42816
	s_waitcnt lgkmcnt(0)
; __device__ __forceinline__ void m3_outputs(const KQ p_in, int e, bool ctx_full, unsigned char* smem, unsigned* scan_word) {
;     ...
;             for (int m = 0; m < 4; ++m)
; #pragma unroll
;                 for (int k2 = 0; k2 < 2; ++k2) {
;                     const bf16x8 af = *(const bf16x8*)(TfT + (16 * m + ln) * 72 + 32 * k2 + 8 * g4);
;                     const bf16x8 ab = *(const bf16x8*)(TbT + (16 * m + ln) * 72 + 32 * k2 + 8 * g4);
;                     O[m] = __builtin_amdgcn_mfma_f32_16x16x32_bf16(af, qff[k2], O[m], 0, 0, 0);
;                     O[m] = __builtin_amdgcn_mfma_f32_16x16x32_bf16(ab, qfb[k2], O[m], 0, 0, 0);
;                     __builtin_amdgcn_sched_barrier(0);
;                 }
;             const float lf2 = lgf * 1.44269504f, lb2 = lgb * 1.44269504f; const int di = i - 4 * g4;
;             const float bfw = lf2 * (float)di, bbw = -lb2 * (float)di;
;             f32x4 st[8];
; #pragma unroll
;             for (int mt = 0; mt < 8; ++mt) {
;                 f32x4 a = (f32x4){0.f, 0.f, 0.f, 0.f};
; #pragma unroll
;                 for (int k2 = 0; k2 < 2; ++k2) { const bf16x8 kf = *(const bf16x8*)(Kt + (16 * mt + ln) * 72 + 32 * k2 + 8 * g4); a = __builtin_amdgcn_mfma_f32_16x16x32_bf16(kf, qf[k2], a, 0, 0, 0); }
; #pragma unroll
;                 for (int rg = 0; rg < 4; ++rg) { const int cc = 16 * mt + rg; const int df = di - cc;
;                     const float arg = (df > 0) ? fmaf(-lf2, (float)cc, bfw) : fmaf(lb2, (float)cc, bbw);
;                     float wgt = __builtin_amdgcn_exp2f(arg); wgt = (df == 0) ? 2.0f : wgt;
;                     a[rg] *= wgt; }
;                 st[mt] = a;
;                 __builtin_amdgcn_sched_barrier(0);
;             }
	v_mfma_f32_16x16x32_bf16 v[16:19], v[28:31], v[32:35], v[16:19]
	ds_read_b128 v[28:31], v116 offset:52032
	s_waitcnt lgkmcnt(0)
	v_mfma_f32_16x16x32_bf16 v[16:19], v[28:31], v[36:39], v[16:19]
	v_add_u32_e32 v33, v111, v117
	ds_read_b128 v[34:37], v33
	ds_read_b128 v[38:41], v33 offset:64
	v_mul_f32_e32 v28, 0xbfb8aa3b, v26
	v_mul_f32_e32 v26, 0xbfb8aa3b, v27
	v_mul_f32_e32 v27, v28, v112
	v_mul_f32_e64 v29, v112, -v26
	v_readlane_b32 s0, v253, 41
	v_fmamk_f32 v30, v28, 0x80000000, v27
	v_fma_f32 v31, 0, v26, v29
	v_readlane_b32 s1, v253, 42
	s_waitcnt lgkmcnt(1)
	v_mfma_f32_16x16x32_bf16 v[34:37], v[34:37], v[0:3], 0
	v_fma_f32 v32, v112, -v26, v26
	v_cndmask_b32_e64 v30, v31, v30, s[0:1]
	v_exp_f32_e32 v30, v30
	v_readlane_b32 s0, v253, 43
	v_readlane_b32 s1, v253, 44
	v_fma_f32 v31, v28, v112, -v28
	s_waitcnt lgkmcnt(0)
	v_mfma_f32_16x16x32_bf16 v[34:37], v[38:41], v[20:23], v[34:37]
	v_cndmask_b32_e64 v30, v30, 2.0, s[0:1]
	v_readlane_b32 s0, v253, 45
	v_readlane_b32 s1, v253, 46
	s_nop 1
	v_cndmask_b32_e64 v31, v32, v31, s[0:1]
	v_exp_f32_e32 v31, v31
	v_readlane_b32 s0, v253, 47
	v_readlane_b32 s1, v253, 48
	v_mul_f32_e32 v30, v30, v34
	v_fma_f32 v32, -2.0, v28, v27
	v_cndmask_b32_e64 v31, v31, 2.0, s[0:1]
	v_readlane_b32 s0, v253, 49
	v_fma_f32 v34, 2.0, v26, v29
	v_readlane_b32 s1, v253, 50
	v_mul_f32_e32 v31, v31, v35
	v_fmamk_f32 v35, v26, 0x40400000, v29
	v_cndmask_b32_e64 v32, v34, v32, s[0:1]
	v_exp_f32_e32 v32, v32
	v_readlane_b32 s0, v253, 51
	v_readlane_b32 s1, v253, 52
	v_fmamk_f32 v34, v28, 0xc0400000, v27
	s_nop 0
	v_cndmask_b32_e64 v32, v32, 2.0, s[0:1]
	v_readlane_b32 s0, v253, 53
	v_readlane_b32 s1, v253, 54
	v_mul_f32_e32 v32, v32, v36
	s_nop 0
	v_cndmask_b32_e64 v34, v35, v34, s[0:1]
	v_exp_f32_e32 v34, v34
	v_readlane_b32 s0, v253, 55
	v_readlane_b32 s1, v253, 56
	s_nop 1
	v_cndmask_b32_e64 v34, v34, 2.0, s[0:1]
	v_mul_f32_e32 v34, v34, v37
	ds_read_b128 v[36:39], v33 offset:2304
	ds_read_b128 v[40:43], v33 offset:2368
	v_readlane_b32 s0, v253, 57
	v_fmamk_f32 v35, v28, 0xc1800000, v27
	v_readlane_b32 s1, v253, 58
	s_waitcnt lgkmcnt(1)
	v_mfma_f32_16x16x32_bf16 v[36:39], v[36:39], v[0:3], 0
	s_waitcnt lgkmcnt(0)
	v_mfma_f32_16x16x32_bf16 v[36:39], v[40:43], v[20:23], v[36:39]
	v_fmamk_f32 v40, v26, 0x41800000, v29
	v_cndmask_b32_e64 v35, v40, v35, s[0:1]
	v_exp_f32_e32 v35, v35
	v_readlane_b32 s0, v253, 59
	v_readlane_b32 s1, v253, 60
	v_fmamk_f32 v40, v26, 0x41880000, v29
	s_nop 0
	v_cndmask_b32_e64 v35, v35, 2.0, s[0:1]
	v_readlane_b32 s0, v253, 61
	v_mul_f32_e32 v35, v35, v36
	v_fmamk_f32 v36, v28, 0xc1880000, v27
	v_readlane_b32 s1, v253, 62
	s_nop 1
	v_cndmask_b32_e64 v36, v40, v36, s[0:1]
	v_exp_f32_e32 v36, v36
	v_readlane_b32 s0, v253, 63
	v_readlane_b32 s1, v254, 0
	v_fmamk_f32 v40, v26, 0x41900000, v29
	s_nop 0
	v_cndmask_b32_e64 v36, v36, 2.0, s[0:1]
	v_readlane_b32 s0, v254, 1
	v_mul_f32_e32 v36, v36, v37
	v_fmamk_f32 v37, v28, 0xc1900000, v27
	v_readlane_b32 s1, v254, 2
	s_nop 1
	v_cndmask_b32_e64 v37, v40, v37, s[0:1]
	v_exp_f32_e32 v37, v37
	v_readlane_b32 s0, v254, 3
	v_readlane_b32 s1, v254, 4
	v_fmamk_f32 v40, v26, 0x41980000, v29
	s_nop 0
	v_cndmask_b32_e64 v37, v37, 2.0, s[0:1]
	v_readlane_b32 s0, v254, 5
	v_mul_f32_e32 v38, v37, v38
	v_fmamk_f32 v37, v28, 0xc1980000, v27
	v_readlane_b32 s1, v254, 6
	s_nop 1
	v_cndmask_b32_e64 v37, v40, v37, s[0:1]
	v_exp_f32_e32 v37, v37
	v_readlane_b32 s0, v254, 7
	v_readlane_b32 s1, v254, 8
	s_nop 1
	v_cndmask_b32_e64 v37, v37, 2.0, s[0:1]
	v_mul_f32_e32 v40, v37, v39
	ds_read_b128 v[42:45], v33 offset:4608
	ds_read_b128 v[46:49], v33 offset:4672
	v_readlane_b32 s0, v254, 9
	v_fmamk_f32 v37, v28, 0xc2000000, v27
	v_fmamk_f32 v39, v26, 0x42000000, v29
	v_readlane_b32 s1, v254, 10
	v_fmamk_f32 v41, v26, 0x42040000, v29
	s_waitcnt lgkmcnt(1)
	v_mfma_f32_16x16x32_bf16 v[42:45], v[42:45], v[0:3], 0
	v_cndmask_b32_e64 v37, v39, v37, s[0:1]
	v_exp_f32_e32 v37, v37
	v_readlane_b32 s0, v254, 11
	v_readlane_b32 s1, v254, 12
	v_fmamk_f32 v39, v28, 0xc2040000, v27
	s_waitcnt lgkmcnt(0)
	v_mfma_f32_16x16x32_bf16 v[42:45], v[46:49], v[20:23], v[42:45]
	v_cndmask_b32_e64 v37, v37, 2.0, s[0:1]
	v_readlane_b32 s0, v254, 13
	v_readlane_b32 s1, v254, 14
	s_nop 1
	v_cndmask_b32_e64 v39, v41, v39, s[0:1]
	v_exp_f32_e32 v39, v39
	v_readlane_b32 s0, v254, 15
	v_readlane_b32 s1, v254, 16
	v_mul_f32_e32 v37, v37, v42
	v_fmamk_f32 v41, v28, 0xc2080000, v27
	v_cndmask_b32_e64 v39, v39, 2.0, s[0:1]
	v_readlane_b32 s0, v254, 17
	v_fmamk_f32 v42, v26, 0x42080000, v29
	v_readlane_b32 s1, v254, 18
	v_mul_f32_e32 v39, v39, v43
	v_fmamk_f32 v43, v26, 0x420c0000, v29
	v_cndmask_b32_e64 v41, v42, v41, s[0:1]
	v_exp_f32_e32 v41, v41
	v_readlane_b32 s0, v254, 19
	v_readlane_b32 s1, v254, 20
	v_fmamk_f32 v42, v28, 0xc20c0000, v27
	s_nop 0
	v_cndmask_b32_e64 v41, v41, 2.0, s[0:1]
	v_readlane_b32 s0, v254, 21
	v_readlane_b32 s1, v254, 22
	v_mul_f32_e32 v41, v41, v44
	s_nop 0
	v_cndmask_b32_e64 v42, v43, v42, s[0:1]
	v_exp_f32_e32 v42, v42
	v_readlane_b32 s0, v254, 23
	v_readlane_b32 s1, v254, 24
	s_nop 1
	v_cndmask_b32_e64 v42, v42, 2.0, s[0:1]
	v_mul_f32_e32 v42, v42, v45
	ds_read_b128 v[44:47], v33 offset:6912
	ds_read_b128 v[48:51], v33 offset:6976
	v_readlane_b32 s0, v254, 25
	v_fmamk_f32 v43, v28, 0xc2400000, v27
	v_readlane_b32 s1, v254, 26
	s_waitcnt lgkmcnt(1)
	v_mfma_f32_16x16x32_bf16 v[44:47], v[44:47], v[0:3], 0
	s_waitcnt lgkmcnt(0)
; __device__ __forceinline__ void m3_outputs(const KQ p_in, int e, bool ctx_full, unsigned char* smem, unsigned* scan_word) {
;     ...
;             for (int mt = 0; mt < 8; ++mt) {
;                 f32x4 a = (f32x4){0.f, 0.f, 0.f, 0.f};
; #pragma unroll
;                 for (int k2 = 0; k2 < 2; ++k2) { const bf16x8 kf = *(const bf16x8*)(Kt + (16 * mt + ln) * 72 + 32 * k2 + 8 * g4); a = __builtin_amdgcn_mfma_f32_16x16x32_bf16(kf, qf[k2], a, 0, 0, 0); }
; #pragma unroll
;                 for (int rg = 0; rg < 4; ++rg) { const int cc = 16 * mt + rg; const int df = di - cc;
;                     const float arg = (df > 0) ? fmaf(-lf2, (float)cc, bfw) : fmaf(lb2, (float)cc, bbw);
;                     float wgt = __builtin_amdgcn_exp2f(arg); wgt = (df == 0) ? 2.0f : wgt;
;                     a[rg] *= wgt; }
;                 st[mt] = a;
;                 __builtin_amdgcn_sched_barrier(0);
;             }
	v_mfma_f32_16x16x32_bf16 v[44:47], v[48:51], v[20:23], v[44:47]
	v_fmamk_f32 v48, v26, 0x42400000, v29
	v_cndmask_b32_e64 v43, v48, v43, s[0:1]
	v_exp_f32_e32 v43, v43
	v_readlane_b32 s0, v254, 27
	v_readlane_b32 s1, v254, 28
	v_fmamk_f32 v48, v26, 0x42440000, v29
	s_nop 0
	v_cndmask_b32_e64 v43, v43, 2.0, s[0:1]
	v_readlane_b32 s0, v254, 29
	v_mul_f32_e32 v43, v43, v44
	v_fmamk_f32 v44, v28, 0xc2440000, v27
	v_readlane_b32 s1, v254, 30
	s_nop 1
	v_cndmask_b32_e64 v44, v48, v44, s[0:1]
	v_exp_f32_e32 v44, v44
	v_readlane_b32 s0, v254, 31
	v_readlane_b32 s1, v254, 32
	v_fmamk_f32 v48, v26, 0x42480000, v29
	s_nop 0
	v_cndmask_b32_e64 v44, v44, 2.0, s[0:1]
	v_readlane_b32 s0, v254, 33
	v_mul_f32_e32 v44, v44, v45
	v_fmamk_f32 v45, v28, 0xc2480000, v27
	v_readlane_b32 s1, v254, 34
	s_nop 1
	v_cndmask_b32_e64 v45, v48, v45, s[0:1]
	v_exp_f32_e32 v45, v45
	v_readlane_b32 s0, v254, 35
	v_readlane_b32 s1, v254, 36
	v_fmamk_f32 v48, v26, 0x424c0000, v29
	s_nop 0
	v_cndmask_b32_e64 v45, v45, 2.0, s[0:1]
	v_readlane_b32 s0, v254, 37
	v_mul_f32_e32 v45, v45, v46
	v_fmamk_f32 v46, v28, 0xc24c0000, v27
	v_readlane_b32 s1, v254, 38
	s_nop 1
	v_cndmask_b32_e64 v46, v48, v46, s[0:1]
	v_exp_f32_e32 v46, v46
	v_readlane_b32 s0, v254, 39
	v_readlane_b32 s1, v254, 40
	s_nop 1
	v_cndmask_b32_e64 v46, v46, 2.0, s[0:1]
	v_mul_f32_e32 v54, v46, v47
	ds_read_b128 v[46:49], v33 offset:9216
	ds_read_b128 v[50:53], v33 offset:9280
	v_readlane_b32 s0, v254, 41
	v_readlane_b32 s1, v254, 42
	s_waitcnt lgkmcnt(1)
	v_mfma_f32_16x16x32_bf16 v[46:49], v[46:49], v[0:3], 0
	s_waitcnt lgkmcnt(0)
	v_mfma_f32_16x16x32_bf16 v[46:49], v[50:53], v[20:23], v[46:49]
	v_fmamk_f32 v50, v28, 0xc2800000, v27
	v_fmamk_f32 v51, v26, 0x42800000, v29
	v_cndmask_b32_e64 v50, v51, v50, s[0:1]
	v_exp_f32_e32 v50, v50
	v_readlane_b32 s0, v254, 43
	v_readlane_b32 s1, v254, 44
	s_nop 1
	v_cndmask_b32_e64 v50, v50, 2.0, s[0:1]
	v_readlane_b32 s0, v254, 45
	v_mul_f32_e32 v55, v50, v46
	v_fmamk_f32 v46, v28, 0xc2820000, v27
	v_fmamk_f32 v50, v26, 0x42820000, v29
	v_readlane_b32 s1, v254, 46
	s_nop 1
	v_cndmask_b32_e64 v46, v50, v46, s[0:1]
	v_exp_f32_e32 v46, v46
	v_readlane_b32 s0, v254, 47
	v_readlane_b32 s1, v254, 48
	s_nop 1
	v_cndmask_b32_e64 v46, v46, 2.0, s[0:1]
	v_readlane_b32 s0, v254, 49
	v_mul_f32_e32 v56, v46, v47
	v_fmamk_f32 v46, v28, 0xc2840000, v27
	v_fmamk_f32 v47, v26, 0x42840000, v29
	v_readlane_b32 s1, v254, 50
	s_nop 1
	v_cndmask_b32_e64 v46, v47, v46, s[0:1]
	v_exp_f32_e32 v46, v46
	v_readlane_b32 s0, v254, 51
	v_readlane_b32 s1, v254, 52
	v_fmamk_f32 v47, v26, 0x42860000, v29
	s_nop 0
	v_cndmask_b32_e64 v46, v46, 2.0, s[0:1]
	v_readlane_b32 s0, v254, 53
	v_mul_f32_e32 v57, v46, v48
	v_fmamk_f32 v46, v28, 0xc2860000, v27
	v_readlane_b32 s1, v254, 54
	s_nop 1
	v_cndmask_b32_e64 v46, v47, v46, s[0:1]
	v_exp_f32_e32 v46, v46
	v_readlane_b32 s0, v254, 55
	v_readlane_b32 s1, v254, 56
	s_nop 1
	v_cndmask_b32_e64 v46, v46, 2.0, s[0:1]
	v_mul_f32_e32 v58, v46, v49
	ds_read_b128 v[46:49], v33 offset:11520
	ds_read_b128 v[50:53], v33 offset:11584
	v_readlane_b32 s0, v254, 57
	v_readlane_b32 s1, v254, 58
	s_waitcnt lgkmcnt(1)
	v_mfma_f32_16x16x32_bf16 v[46:49], v[46:49], v[0:3], 0
	s_waitcnt lgkmcnt(0)
	v_mfma_f32_16x16x32_bf16 v[46:49], v[50:53], v[20:23], v[46:49]
	v_fmamk_f32 v50, v28, 0xc2a00000, v27
	v_fmamk_f32 v51, v26, 0x42a00000, v29
	v_cndmask_b32_e64 v50, v51, v50, s[0:1]
	v_exp_f32_e32 v50, v50
	v_readlane_b32 s0, v254, 59
	v_readlane_b32 s1, v254, 60
	s_nop 1
	v_cndmask_b32_e64 v50, v50, 2.0, s[0:1]
	v_readlane_b32 s0, v254, 61
	v_mul_f32_e32 v59, v50, v46
	v_fmamk_f32 v46, v28, 0xc2a20000, v27
	v_fmamk_f32 v50, v26, 0x42a20000, v29
	v_readlane_b32 s1, v254, 62
	s_nop 1
	v_cndmask_b32_e64 v46, v50, v46, s[0:1]
	v_exp_f32_e32 v46, v46
	v_readlane_b32 s0, v254, 63
	v_readlane_b32 s1, v255, 0
	s_nop 1
	v_cndmask_b32_e64 v46, v46, 2.0, s[0:1]
	v_readlane_b32 s0, v255, 1
	v_mul_f32_e32 v60, v46, v47
	v_fmamk_f32 v46, v28, 0xc2a40000, v27
	v_fmamk_f32 v47, v26, 0x42a40000, v29
	v_readlane_b32 s1, v255, 2
	s_nop 1
	v_cndmask_b32_e64 v46, v47, v46, s[0:1]
	v_exp_f32_e32 v46, v46
	v_readlane_b32 s0, v255, 3
	v_readlane_b32 s1, v255, 4
	v_fmamk_f32 v47, v26, 0x42a60000, v29
	s_nop 0
	v_cndmask_b32_e64 v46, v46, 2.0, s[0:1]
	v_readlane_b32 s0, v255, 5
	v_mul_f32_e32 v61, v46, v48
	v_fmamk_f32 v46, v28, 0xc2a60000, v27
	v_readlane_b32 s1, v255, 6
	s_nop 1
	v_cndmask_b32_e64 v46, v47, v46, s[0:1]
	v_exp_f32_e32 v46, v46
	v_readlane_b32 s0, v255, 7
	v_readlane_b32 s1, v255, 8
	s_nop 1
	v_cndmask_b32_e64 v46, v46, 2.0, s[0:1]
	v_mul_f32_e32 v62, v46, v49
	ds_read_b128 v[46:49], v33 offset:13824
	ds_read_b128 v[50:53], v33 offset:13888
	v_readlane_b32 s0, v255, 9
	v_readlane_b32 s1, v255, 10
	s_waitcnt lgkmcnt(1)
	v_mfma_f32_16x16x32_bf16 v[46:49], v[46:49], v[0:3], 0
	s_waitcnt lgkmcnt(0)
	v_mfma_f32_16x16x32_bf16 v[46:49], v[50:53], v[20:23], v[46:49]
	v_fmamk_f32 v50, v28, 0xc2c00000, v27
	v_fmamk_f32 v51, v26, 0x42c00000, v29
	v_cndmask_b32_e64 v50, v51, v50, s[0:1]
	v_exp_f32_e32 v50, v50
	v_readlane_b32 s0, v255, 11
	v_readlane_b32 s1, v255, 12
	v_fmamk_f32 v51, v26, 0x42c20000, v29
	s_nop 0
	v_cndmask_b32_e64 v50, v50, 2.0, s[0:1]
	v_readlane_b32 s0, v255, 13
	v_mul_f32_e32 v50, v50, v46
	v_fmamk_f32 v46, v28, 0xc2c20000, v27
	v_readlane_b32 s1, v255, 14
	s_nop 1
	v_cndmask_b32_e64 v46, v51, v46, s[0:1]
	v_exp_f32_e32 v46, v46
	v_readlane_b32 s0, v255, 15
	v_readlane_b32 s1, v255, 16
	s_nop 1
	v_cndmask_b32_e64 v46, v46, 2.0, s[0:1]
	v_readlane_b32 s0, v255, 17
	v_mul_f32_e32 v51, v46, v47
	v_fmamk_f32 v46, v28, 0xc2c40000, v27
	v_fmamk_f32 v47, v26, 0x42c40000, v29
	v_readlane_b32 s1, v255, 18
	s_nop 1
	v_cndmask_b32_e64 v46, v47, v46, s[0:1]
	v_exp_f32_e32 v46, v46
	v_readlane_b32 s0, v255, 19
	v_readlane_b32 s1, v255, 20
	v_fmamk_f32 v47, v26, 0x42c60000, v29
	s_nop 0
	v_cndmask_b32_e64 v46, v46, 2.0, s[0:1]
	v_readlane_b32 s0, v255, 21
	v_mul_f32_e32 v52, v46, v48
	v_fmamk_f32 v46, v28, 0xc2c60000, v27
	v_readlane_b32 s1, v255, 22
	s_nop 1
	v_cndmask_b32_e64 v46, v47, v46, s[0:1]
	v_exp_f32_e32 v46, v46
	v_readlane_b32 s0, v255, 23
	v_readlane_b32 s1, v255, 24
	s_nop 1
	v_cndmask_b32_e64 v46, v46, 2.0, s[0:1]
	v_mul_f32_e32 v53, v46, v49
	ds_read_b128 v[46:49], v33 offset:16128
	s_waitcnt lgkmcnt(0)
; __device__ __forceinline__ void m3_outputs(const KQ p_in, int e, bool ctx_full, unsigned char* smem, unsigned* scan_word) {
;     ...
;             for (int mt = 0; mt < 8; ++mt) {
;                 f32x4 a = (f32x4){0.f, 0.f, 0.f, 0.f};
; #pragma unroll
;                 for (int k2 = 0; k2 < 2; ++k2) { const bf16x8 kf = *(const bf16x8*)(Kt + (16 * mt + ln) * 72 + 32 * k2 + 8 * g4); a = __builtin_amdgcn_mfma_f32_16x16x32_bf16(kf, qf[k2], a, 0, 0, 0); }
; #pragma unroll
;                 for (int rg = 0; rg < 4; ++rg) { const int cc = 16 * mt + rg; const int df = di - cc;
;                     const float arg = (df > 0) ? fmaf(-lf2, (float)cc, bfw) : fmaf(lb2, (float)cc, bbw);
;                     float wgt = __builtin_amdgcn_exp2f(arg); wgt = (df == 0) ? 2.0f : wgt;
;                     a[rg] *= wgt; }
;                 st[mt] = a;
;                 __builtin_amdgcn_sched_barrier(0);
;             }
; #pragma unroll
;             for (int ks = 0; ks < 4; ++ks) {
;                 const bf16x8 pfr = pack8(st[2 * ks], st[2 * ks + 1]);
; #pragma unroll
;                 for (int m = 0; m < 4; ++m) {
;                     const int vrow = 16 * m + ln; const int kx = (32 * ks + 4 * g4) ^ (((vrow >> 3) & 7) << 2);
;                     const bf16_t* vr = Vt + vrow * 136;
;                     const bf16x4 v0 = *(const bf16x4*)(vr + kx), v1 = *(const bf16x4*)(vr + (kx ^ 16));
;                     const bf16x8 vf = __builtin_shufflevector(v0, v1, 0, 1, 2, 3, 4, 5, 6, 7);
;                     O[m] = __builtin_amdgcn_mfma_f32_16x16x32_bf16(vf, pfr, O[m], 0, 0, 0);
;                 }
;                 __builtin_amdgcn_sched_barrier(0);
;             }
;             float ss = 0.f;
; #pragma unroll
;             for (int m = 0; m < 4; ++m)
; #pragma unroll
;                 for (int rg = 0; rg < 4; ++rg) ss += O[m][rg] * O[m][rg];
;             ss += __shfl_xor(ss, 16, 64); ss += __shfl_xor(ss, 32, 64);
	v_mfma_f32_16x16x32_bf16 v[0:3], v[46:49], v[0:3], 0
	ds_read_b128 v[46:49], v33 offset:16192
	s_waitcnt lgkmcnt(0)
	v_mfma_f32_16x16x32_bf16 v[0:3], v[46:49], v[20:23], v[0:3]
	v_fmamk_f32 v20, v28, 0xc2e00000, v27
	v_fmamk_f32 v21, v26, 0x42e00000, v29
	v_cndmask_b32_e64 v20, v21, v20, s[16:17]
	v_exp_f32_e32 v20, v20
	s_nop 0
	v_cndmask_b32_e64 v20, v20, 2.0, s[18:19]
	s_nop 1
	v_mul_f32_e32 v33, v20, v0
	v_fmamk_f32 v0, v28, 0xc2e20000, v27
	v_fmamk_f32 v20, v26, 0x42e20000, v29
	v_cndmask_b32_e64 v0, v20, v0, s[20:21]
	v_exp_f32_e32 v0, v0
	s_nop 0
	v_cndmask_b32_e64 v0, v0, 2.0, s[22:23]
	v_mul_f32_e32 v46, v0, v1
	v_fmamk_f32 v0, v28, 0xc2e40000, v27
	v_fmamk_f32 v1, v26, 0x42e40000, v29
	v_cndmask_b32_e64 v0, v1, v0, s[24:25]
	v_exp_f32_e32 v0, v0
	v_fmac_f32_e32 v27, 0xc2e60000, v28
	v_fmac_f32_e32 v29, 0x42e60000, v26
	v_cndmask_b32_e64 v0, v0, 2.0, s[26:27]
	v_mul_f32_e32 v47, v0, v2
	v_cndmask_b32_e64 v0, v29, v27, s[28:29]
	v_exp_f32_e32 v0, v0
	s_nop 0
	v_cndmask_b32_e64 v0, v0, 2.0, s[30:31]
	v_mul_f32_e32 v26, v0, v3
	v_add_u32_e32 v20, 0x4800, v118
	v_cvt_pk_bf16_f32 v0, v30, v31
	v_cvt_pk_bf16_f32 v1, v32, v34
	v_cvt_pk_bf16_f32 v2, v35, v36
	v_cvt_pk_bf16_f32 v3, v38, v40
	ds_read2_b64 v[20:23], v20 offset1:4
	s_waitcnt lgkmcnt(0)
	v_mfma_f32_16x16x32_bf16 v[4:7], v[20:23], v[0:3], v[4:7]
	v_add_u32_e32 v20, 0x4800, v119
	ds_read2_b64 v[20:23], v20 offset1:4
	s_waitcnt lgkmcnt(0)
	v_mfma_f32_16x16x32_bf16 v[8:11], v[20:23], v[0:3], v[8:11]
	ds_read_b64 v[20:21], v120 offset:18432
	ds_read_b64 v[22:23], v121 offset:18432
	s_waitcnt lgkmcnt(0)
	v_mfma_f32_16x16x32_bf16 v[12:15], v[20:23], v[0:3], v[12:15]
	ds_read_b64 v[20:21], v122 offset:18432
	ds_read_b64 v[22:23], v123 offset:18432
	s_waitcnt lgkmcnt(0)
	v_mfma_f32_16x16x32_bf16 v[0:3], v[20:23], v[0:3], v[16:19]
	v_add_u32_e32 v20, 0x4800, v125
	v_cvt_pk_bf16_f32 v16, v37, v39
	v_cvt_pk_bf16_f32 v17, v41, v42
	v_cvt_pk_bf16_f32 v18, v43, v44
	v_cvt_pk_bf16_f32 v19, v45, v54
	ds_read2_b64 v[20:23], v20 offset1:4
	s_waitcnt lgkmcnt(0)
	v_mfma_f32_16x16x32_bf16 v[4:7], v[20:23], v[16:19], v[4:7]
	v_add_u32_e32 v20, 0x4800, v126
	ds_read2_b64 v[20:23], v20 offset1:4
	s_waitcnt lgkmcnt(0)
	v_mfma_f32_16x16x32_bf16 v[8:11], v[20:23], v[16:19], v[8:11]
	ds_read_b64 v[20:21], v127 offset:18432
	ds_read_b64 v[22:23], v128 offset:18432
	s_waitcnt lgkmcnt(0)
	v_mfma_f32_16x16x32_bf16 v[12:15], v[20:23], v[16:19], v[12:15]
	ds_read_b64 v[20:21], v129 offset:18432
	ds_read_b64 v[22:23], v130 offset:18432
	s_waitcnt lgkmcnt(0)
	v_mfma_f32_16x16x32_bf16 v[0:3], v[20:23], v[16:19], v[0:3]
	v_add_u32_e32 v20, 0x4800, v132
	v_cvt_pk_bf16_f32 v16, v55, v56
	v_cvt_pk_bf16_f32 v17, v57, v58
	v_cvt_pk_bf16_f32 v18, v59, v60
	v_cvt_pk_bf16_f32 v19, v61, v62
	ds_read2_b64 v[20:23], v20 offset1:4
	s_waitcnt lgkmcnt(0)
	v_mfma_f32_16x16x32_bf16 v[4:7], v[20:23], v[16:19], v[4:7]
	v_add_u32_e32 v20, 0x4800, v133
	ds_read2_b64 v[20:23], v20 offset1:4
	s_waitcnt lgkmcnt(0)
	v_mfma_f32_16x16x32_bf16 v[8:11], v[20:23], v[16:19], v[8:11]
	ds_read_b64 v[20:21], v134 offset:18432
	ds_read_b64 v[22:23], v135 offset:18432
	s_waitcnt lgkmcnt(0)
	v_mfma_f32_16x16x32_bf16 v[20:23], v[20:23], v[16:19], v[12:15]
	s_nop 2
	ds_read_b64 v[12:13], v136 offset:18432
	ds_read_b64 v[14:15], v137 offset:18432
	s_waitcnt lgkmcnt(0)
	v_mfma_f32_16x16x32_bf16 v[0:3], v[12:15], v[16:19], v[0:3]
	v_add_u32_e32 v12, 0x4800, v139
	v_cvt_pk_bf16_f32 v16, v50, v51
	v_cvt_pk_bf16_f32 v17, v52, v53
	v_cvt_pk_bf16_f32 v18, v33, v46
	v_cvt_pk_bf16_f32 v19, v47, v26
	ds_read2_b64 v[12:15], v12 offset1:4
	s_waitcnt lgkmcnt(0)
	v_mfma_f32_16x16x32_bf16 v[12:15], v[12:15], v[16:19], v[4:7]
	s_nop 2
	v_add_u32_e32 v4, 0x4800, v140
	ds_read2_b64 v[4:7], v4 offset1:4
	s_waitcnt lgkmcnt(0)
	v_mfma_f32_16x16x32_bf16 v[8:11], v[4:7], v[16:19], v[8:11]
	ds_read_b64 v[4:5], v141 offset:18432
	ds_read_b64 v[6:7], v142 offset:18432
	s_waitcnt lgkmcnt(0)
	v_mfma_f32_16x16x32_bf16 v[4:7], v[4:7], v[16:19], v[20:23]
	s_nop 2
	ds_read_b64 v[20:21], v143 offset:18432
	ds_read_b64 v[22:23], v154 offset:18432
	s_waitcnt lgkmcnt(0)
	v_mfma_f32_16x16x32_bf16 v[0:3], v[20:23], v[16:19], v[0:3]
	v_mul_f32_e32 v20, v13, v13
	v_fmac_f32_e32 v20, v12, v12
	v_fmac_f32_e32 v20, v14, v14
	v_fmac_f32_e32 v20, v15, v15
	v_fmac_f32_e32 v20, v8, v8
	v_fmac_f32_e32 v20, v9, v9
	v_fmac_f32_e32 v20, v10, v10
	v_fmac_f32_e32 v20, v11, v11
	v_pk_mul_f32 v[18:19], v[4:5], v[4:5]
	v_pk_mul_f32 v[16:17], v[6:7], v[6:7]
	v_add_f32_e32 v18, v18, v20
	v_add_f32_e32 v18, v19, v18
	v_add_f32_e32 v16, v16, v18
	v_add_f32_e32 v20, v17, v16
	v_pk_mul_f32 v[18:19], v[0:1], v[0:1]
	v_pk_mul_f32 v[16:17], v[2:3], v[2:3]
	v_add_f32_e32 v18, v18, v20
	v_add_f32_e32 v18, v19, v18
	v_add_f32_e32 v16, v16, v18
	v_and_b32_e32 v18, 64, v205
	v_add_f32_e32 v16, v17, v16
	v_xor_b32_e32 v17, 16, v205
	v_add_u32_e32 v18, 64, v18
	v_cmp_lt_i32_e32 vcc, v17, v18
	v_lshlrev_b32_e32 v20, 1, v86
	v_mov_b32_e32 v21, v145
	v_cndmask_b32_e32 v17, v205, v17, vcc
	v_lshlrev_b32_e32 v17, 2, v17
	ds_bpermute_b32 v17, v17, v16
	s_waitcnt lgkmcnt(0)
	v_add_f32_e32 v16, v16, v17
	v_xor_b32_e32 v17, 32, v205
	v_cmp_lt_i32_e32 vcc, v17, v18
	s_nop 1
	v_cndmask_b32_e32 v17, v205, v17, vcc
	v_lshlrev_b32_e32 v17, 2, v17
	ds_bpermute_b32 v17, v17, v16
	s_waitcnt lgkmcnt(0)
; __device__ __forceinline__ float bf2f(bf16_t b) { return __uint_as_float(((unsigned)b) << 16); }
; __device__ __forceinline__ float silu_f(float x) { return x * __builtin_amdgcn_rcpf(1.0f + __expf(-x)); }
; __device__ __forceinline__ unsigned cvt_pk_bf16(float lo, float hi) { unsigned r; asm volatile("v_cvt_pk_bf16_f32 %0, %1, %2" : "=v"(r) : "v"(lo), "v"(hi)); return r; }
; __device__ __forceinline__ void m3_outputs(const KQ p_in, int e, bool ctx_full, unsigned char* smem, unsigned* scan_word) {
;     ...
;             ss += __shfl_xor(ss, 16, 64); ss += __shfl_xor(ss, 32, 64);
;             const float rn = rsqrtf(ss * (1.0f / 64.0f) + EPS);
; #pragma unroll
;             for (int m = 0; m < 4; ++m) {
;                 const int ee = 16 * m + 4 * g4;
;                 const bf16x4 gv = *(const bf16x4*)(Z + (size_t)(t0 + i) * INW + 1024 + h * 64 + ee);
;                 uint2 o2; o2.x = pg8::cvt_pk_bf16(O[m][0] * rn * silu_f(bf2f((bf16_t)gv[0])), O[m][1] * rn * silu_f(bf2f((bf16_t)gv[1])));
;                 o2.y = pg8::cvt_pk_bf16(O[m][2] * rn * silu_f(bf2f((bf16_t)gv[2])), O[m][3] * rn * silu_f(bf2f((bf16_t)gv[3])));
;                 *(uint2*)(MIX + (size_t)(t0 + i) * D + 512 + h * 64 + ee) = o2;
;             }
	v_add_f32_e32 v16, v16, v17
	v_fmamk_f32 v16, v16, 0x3c800000, v146
	v_cmp_gt_f32_e32 vcc, s67, v16
	v_mul_f32_e32 v17, 0x4b800000, v16
	s_nop 0
	v_cndmask_b32_e32 v16, v16, v17, vcc
	v_rsq_f32_e32 v16, v16
	s_nop 0
	v_mul_f32_e32 v17, 0x45800000, v16
	v_cndmask_b32_e32 v26, v16, v17, vcc
	v_lshlrev_b64 v[16:17], 11, v[106:107]
	v_lshl_add_u64 v[16:17], s[90:91], 0, v[16:17]
	v_lshl_add_u64 v[18:19], v[16:17], 0, s[80:81]
	v_lshl_add_u64 v[16:17], v[24:25], 0, v[20:21]
	global_load_dwordx2 v[22:23], v[16:17], off offset:2048
	global_load_dwordx2 v[28:29], v[16:17], off offset:2080
	global_load_dwordx2 v[30:31], v[16:17], off offset:2112
	global_load_dwordx2 v[32:33], v[16:17], off offset:2144
	v_mul_f32_e32 v12, v12, v26
	v_mul_f32_e32 v13, v13, v26
	v_mul_f32_e32 v8, v8, v26
	v_mul_f32_e32 v9, v9, v26
	v_mul_f32_e32 v4, v4, v26
	v_mul_f32_e32 v5, v5, v26
	v_mul_f32_e32 v0, v0, v26
	v_mul_f32_e32 v1, v1, v26
	s_waitcnt lgkmcnt(0)
	s_waitcnt vmcnt(0)
	v_lshlrev_b32_e32 v24, 16, v22
	v_mul_f32_e32 v25, 0xbfb8aa3b, v24
	v_exp_f32_e32 v25, v25
	v_and_b32_e32 v22, 0xffff0000, v22
	v_add_f32_e32 v25, 1.0, v25
	v_rcp_f32_e32 v25, v25
	s_nop 0
	v_mul_f32_e32 v24, v25, v24
	v_mul_f32_e32 v12, v24, v12
	v_mul_f32_e32 v24, 0xbfb8aa3b, v22
	v_exp_f32_e32 v24, v24
	s_nop 0
	v_add_f32_e32 v24, 1.0, v24
	v_rcp_f32_e32 v24, v24
	s_nop 0
	v_mul_f32_e32 v22, v24, v22
	v_mul_f32_e32 v13, v22, v13
	v_cvt_pk_bf16_f32 v22, v12, v13
	v_lshlrev_b32_e32 v13, 16, v23
	v_mul_f32_e32 v12, v14, v26
	v_mul_f32_e32 v14, 0xbfb8aa3b, v13
	v_exp_f32_e32 v14, v14
	s_nop 0
	v_add_f32_e32 v14, 1.0, v14
	v_rcp_f32_e32 v14, v14
	s_nop 0
	v_mul_f32_e32 v13, v14, v13
	v_and_b32_e32 v14, 0xffff0000, v23
	v_mul_f32_e32 v12, v13, v12
	v_mul_f32_e32 v13, v15, v26
	v_mul_f32_e32 v15, 0xbfb8aa3b, v14
	v_exp_f32_e32 v15, v15
	s_nop 0
	v_add_f32_e32 v15, 1.0, v15
	v_rcp_f32_e32 v15, v15
	s_nop 0
	v_mul_f32_e32 v14, v15, v14
	v_mul_f32_e32 v13, v14, v13
	v_cvt_pk_bf16_f32 v23, v12, v13
	v_mov_b32_e32 v14, v28
	v_mov_b32_e32 v15, v29
	v_lshl_add_u64 v[12:13], v[18:19], 0, v[20:21]
	global_store_dwordx2 v[12:13], v[22:23], off offset:1024
	s_waitcnt lgkmcnt(0)
	s_waitcnt vmcnt(1)
	v_lshlrev_b32_e32 v18, 16, v14
	v_mul_f32_e32 v19, 0xbfb8aa3b, v18
	v_exp_f32_e32 v19, v19
	v_and_b32_e32 v14, 0xffff0000, v14
	v_add_f32_e32 v19, 1.0, v19
	v_rcp_f32_e32 v19, v19
	s_nop 0
	v_mul_f32_e32 v18, v19, v18
	v_mul_f32_e32 v8, v8, v18
	v_mul_f32_e32 v18, 0xbfb8aa3b, v14
	v_exp_f32_e32 v18, v18
	s_nop 0
	v_add_f32_e32 v18, 1.0, v18
	v_rcp_f32_e32 v18, v18
	s_nop 0
	v_mul_f32_e32 v14, v18, v14
	v_mul_f32_e32 v9, v9, v14
	v_cvt_pk_bf16_f32 v8, v8, v9
	v_mul_f32_e32 v9, v10, v26
	v_lshlrev_b32_e32 v10, 16, v15
	v_mul_f32_e32 v14, 0xbfb8aa3b, v10
	v_exp_f32_e32 v14, v14
	s_nop 0
	v_add_f32_e32 v14, 1.0, v14
	v_rcp_f32_e32 v14, v14
	s_nop 0
	v_mul_f32_e32 v10, v14, v10
	v_mul_f32_e32 v9, v9, v10
	v_mul_f32_e32 v10, v11, v26
	v_and_b32_e32 v11, 0xffff0000, v15
	v_mul_f32_e32 v14, 0xbfb8aa3b, v11
	v_exp_f32_e32 v14, v14
	s_nop 0
	v_add_f32_e32 v14, 1.0, v14
	v_rcp_f32_e32 v14, v14
	s_nop 0
	v_mul_f32_e32 v11, v14, v11
	v_mul_f32_e32 v10, v10, v11
	v_cvt_pk_bf16_f32 v9, v9, v10
	global_store_dwordx2 v[12:13], v[8:9], off offset:1056
	v_mov_b32_e32 v8, v30
	v_mov_b32_e32 v9, v31
	s_waitcnt lgkmcnt(0)
	s_waitcnt vmcnt(0)
	v_lshlrev_b32_e32 v10, 16, v8
	v_mul_f32_e32 v11, 0xbfb8aa3b, v10
	v_exp_f32_e32 v11, v11
	v_and_b32_e32 v8, 0xffff0000, v8
	v_add_f32_e32 v11, 1.0, v11
	v_rcp_f32_e32 v11, v11
	s_nop 0
	v_mul_f32_e32 v10, v11, v10
	v_mul_f32_e32 v4, v4, v10
	v_mul_f32_e32 v10, 0xbfb8aa3b, v8
	v_exp_f32_e32 v10, v10
	s_nop 0
	v_add_f32_e32 v10, 1.0, v10
	v_rcp_f32_e32 v10, v10
	s_nop 0
	v_mul_f32_e32 v8, v10, v8
	v_mul_f32_e32 v5, v5, v8
	v_cvt_pk_bf16_f32 v4, v4, v5
	v_mul_f32_e32 v5, v6, v26
	v_lshlrev_b32_e32 v6, 16, v9
	v_mul_f32_e32 v8, 0xbfb8aa3b, v6
	v_exp_f32_e32 v8, v8
	s_nop 0
	v_add_f32_e32 v8, 1.0, v8
	v_rcp_f32_e32 v8, v8
	s_nop 0
	v_mul_f32_e32 v6, v8, v6
	v_mul_f32_e32 v5, v5, v6
	v_mul_f32_e32 v6, v7, v26
	v_and_b32_e32 v7, 0xffff0000, v9
	v_mul_f32_e32 v8, 0xbfb8aa3b, v7
	v_exp_f32_e32 v8, v8
	s_nop 0
	v_add_f32_e32 v8, 1.0, v8
	v_rcp_f32_e32 v8, v8
	s_nop 0
	v_mul_f32_e32 v7, v8, v7
	v_mul_f32_e32 v6, v6, v7
	v_cvt_pk_bf16_f32 v5, v5, v6
	global_store_dwordx2 v[12:13], v[4:5], off offset:1088
	v_mov_b32_e32 v4, v32
	v_mov_b32_e32 v5, v33
	s_waitcnt lgkmcnt(0)
	s_waitcnt vmcnt(0)
	v_lshlrev_b32_e32 v6, 16, v4
	v_mul_f32_e32 v7, 0xbfb8aa3b, v6
	v_exp_f32_e32 v7, v7
	v_and_b32_e32 v4, 0xffff0000, v4
	v_add_f32_e32 v7, 1.0, v7
	v_rcp_f32_e32 v7, v7
	s_nop 0
	v_mul_f32_e32 v6, v7, v6
	v_mul_f32_e32 v0, v0, v6
	v_mul_f32_e32 v6, 0xbfb8aa3b, v4
	v_exp_f32_e32 v6, v6
	s_nop 0
	v_add_f32_e32 v6, 1.0, v6
	v_rcp_f32_e32 v6, v6
	s_nop 0
	v_mul_f32_e32 v4, v6, v4
	v_mul_f32_e32 v1, v1, v4
	v_cvt_pk_bf16_f32 v0, v0, v1
	v_mul_f32_e32 v1, v2, v26
	v_lshlrev_b32_e32 v2, 16, v5
	v_mul_f32_e32 v4, 0xbfb8aa3b, v2
	v_exp_f32_e32 v4, v4
	s_nop 0
	v_add_f32_e32 v4, 1.0, v4
	v_rcp_f32_e32 v4, v4
	s_nop 0
	v_mul_f32_e32 v2, v4, v2
	v_mul_f32_e32 v1, v1, v2
	v_mul_f32_e32 v2, v3, v26
	v_and_b32_e32 v3, 0xffff0000, v5
	v_mul_f32_e32 v4, 0xbfb8aa3b, v3
	v_exp_f32_e32 v4, v4
	s_nop 0
	v_add_f32_e32 v4, 1.0, v4
	v_rcp_f32_e32 v4, v4
	s_nop 0
	v_mul_f32_e32 v3, v4, v3
	v_mul_f32_e32 v2, v2, v3
	v_cvt_pk_bf16_f32 v1, v1, v2
	global_store_dwordx2 v[12:13], v[0:1], off offset:1120
	s_cbranch_execnz .LBB0_933
	s_branch .LBB0_963

; __device__ __forceinline__ float bf2f(bf16_t b) { return __uint_as_float(((unsigned)b) << 16); }
; __device__ __forceinline__ void rowphase(const KQ p_in, int Mupd, const bf16_t* Y, int lu, int gidx, float wgt, const float* gpost,
;                          int Mnext, int ln, const float* gpre, int shidx, int scidx, bf16_t* Hout, bool from_input, int tbeg) {
;     ...
;     for (int t = tbeg + (blockIdx.x * 8 + w) * 2; t < Mmax; t += gridDim.x * 16) {
;         float* xr = xrow(p, t); const int mr = modrow(t);
;         const float* xs = xr;
;         if (from_input) xs = (t < TL) ? pin_ld(0) + (size_t)t * D : pin_ld(2) + (size_t)(t - TL) * D;
;         float4 xv[2][4];
; #pragma unroll
;         for (int rr = 0; rr < 2; ++rr)
; #pragma unroll
;             for (int q = 0; q < 4; ++q) xv[rr][q] = *(const float4*)(xs + rr * D + q * 256 + lane * 4);
;         if (Y != nullptr && t < Mupd) {
;             float4 yv[2][4]; float ss[2] = {0.f, 0.f};
; #pragma unroll
;             for (int rr = 0; rr < 2; ++rr)
; #pragma unroll
;                 for (int q = 0; q < 4; ++q) {
;                     if (t < TL) { const bf16x4 yb = *(const bf16x4*)(Y + (size_t)(t + rr) * D + q * 256 + lane * 4);
;                         yv[rr][q] = make_float4(bf2f((bf16_t)yb[0]), bf2f((bf16_t)yb[1]), bf2f((bf16_t)yb[2]), bf2f((bf16_t)yb[3])); }
;                     else { const float* yp = (const float*)(p.ws + WS_YP) + (size_t)(t + rr - TL) * D + q * 256 + lane * 4;
;                         const float4 a0 = *(const float4*)yp, a1 = *(const float4*)(yp + (size_t)TC * D), a2 = *(const float4*)(yp + (size_t)2 * TC * D), a3 = *(const float4*)(yp + (size_t)3 * TC * D);
;                         yv[rr][q] = make_float4(a0.x + a1.x + a2.x + a3.x, a0.y + a1.y + a2.y + a3.y, a0.z + a1.z + a2.z + a3.z, a0.w + a1.w + a2.w + a3.w); }
;                     ss[rr] += yv[rr][q].x * yv[rr][q].x + yv[rr][q].y * yv[rr][q].y + yv[rr][q].z * yv[rr][q].z + yv[rr][q].w * yv[rr][q].w; }
.LBB0_1195:
	v_lshlrev_b32_e32 v34, 2, v40
	v_mov_b32_e32 v35, v145
	v_lshl_add_u64 v[4:5], v[0:1], 0, v[34:35]
	global_load_dwordx4 v[24:27], v[4:5], off
	s_waitcnt vmcnt(1)
	global_load_dwordx4 v[16:19], v[4:5], off offset:1024
	global_load_dwordx4 v[8:11], v[4:5], off offset:2048
	global_load_dwordx4 v[0:3], v[4:5], off offset:3072
	v_add_co_u32_e32 v4, vcc, s42, v4
	v_min_i32_e32 v35, 0x4000, v56
	s_nop 0
	v_addc_co_u32_e32 v5, vcc, 0, v5, vcc
	global_load_dwordx4 v[28:31], v[4:5], off
	global_load_dwordx4 v[20:23], v[4:5], off offset:1024
	global_load_dwordx4 v[12:15], v[4:5], off offset:2048
	s_nop 0
	global_load_dwordx4 v[4:7], v[4:5], off offset:3072
	v_ashrrev_i32_e32 v41, 12, v35
	v_cmp_gt_i32_e32 vcc, s63, v56
	v_lshlrev_b64 v[54:55], 11, v[56:57]
	s_and_saveexec_b64 s[20:21], vcc
	s_waitcnt vmcnt(7)
	s_cbranch_execz .LBB0_1229
	v_lshlrev_b64 v[36:37], 12, v[144:145]
	v_lshl_add_u64 v[36:37], v[42:43], 0, v[36:37]
	s_and_saveexec_b64 s[22:23], s[0:1]
	s_xor_b64 s[22:23], exec, s[22:23]
	s_cbranch_execz .LBB0_1198
	v_add_co_u32_e32 v38, vcc, 0x400000, v36
	s_nop 1
	v_addc_co_u32_e32 v39, vcc, 0, v37, vcc
	global_load_dwordx4 v[58:61], v[36:37], off
	global_load_dwordx4 v[62:65], v[38:39], off
	v_add_co_u32_e32 v38, vcc, 0x800000, v36
	s_nop 1
	v_addc_co_u32_e32 v39, vcc, 0, v37, vcc
	global_load_dwordx4 v[66:69], v[38:39], off
	v_add_co_u32_e32 v38, vcc, 0xc00000, v36
	s_nop 1
	v_addc_co_u32_e32 v39, vcc, 0, v37, vcc
	global_load_dwordx4 v[70:73], v[38:39], off
	v_add_co_u32_e32 v110, vcc, 0x400000, v36
	s_nop 1
	v_addc_co_u32_e32 v111, vcc, 0, v37, vcc
	v_add_co_u32_e32 v112, vcc, 0x800000, v36
	s_nop 1
	v_addc_co_u32_e32 v113, vcc, 0, v37, vcc
	v_add_co_u32_e32 v114, vcc, 0xc00000, v36
	s_nop 1
	v_addc_co_u32_e32 v115, vcc, 0, v37, vcc
	global_load_dwordx4 v[208:211], v[36:37], off offset:1024
	global_load_dwordx4 v[212:215], v[110:111], off offset:1024
	global_load_dwordx4 v[216:219], v[112:113], off offset:1024
	global_load_dwordx4 v[220:223], v[114:115], off offset:1024
	global_load_dwordx4 v[224:227], v[36:37], off offset:2048
	global_load_dwordx4 v[228:231], v[110:111], off offset:2048
	global_load_dwordx4 v[232:235], v[112:113], off offset:2048
	global_load_dwordx4 v[236:239], v[114:115], off offset:2048
	global_load_dwordx4 v[240:243], v[36:37], off offset:3072
	global_load_dwordx4 v[244:247], v[110:111], off offset:3072
	global_load_dwordx4 v[102:105], v[112:113], off offset:3072
	global_load_dwordx4 v[106:109], v[114:115], off offset:3072
	s_waitcnt lgkmcnt(0)
	s_waitcnt vmcnt(14)
	v_pk_add_f32 v[38:39], v[58:59], v[62:63]
	v_pk_add_f32 v[58:59], v[60:61], v[64:65]
	s_waitcnt vmcnt(13)
	v_pk_add_f32 v[38:39], v[38:39], v[66:67]
	v_pk_add_f32 v[60:61], v[58:59], v[68:69]
	s_waitcnt vmcnt(12)
	v_pk_add_f32 v[58:59], v[38:39], v[70:71]
	v_pk_add_f32 v[60:61], v[60:61], v[72:73]
	s_or_saveexec_b64 s[22:23], s[22:23]
	v_lshl_add_u64 v[38:39], v[44:45], 0, v[54:55]
	s_xor_b64 exec, exec, s[22:23]
	s_cbranch_execz .LBB0_1200
	s_branch .LBB0_1199

; __device__ __forceinline__ void rowphase(const KQ p_in, int Mupd, const bf16_t* Y, int lu, int gidx, float wgt, const float* gpost,
;                          int Mnext, int ln, const float* gpre, int shidx, int scidx, bf16_t* Hout, bool from_input, int tbeg) {
;     ...
;                     else { const float* yp = (const float*)(p.ws + WS_YP) + (size_t)(t + rr - TL) * D + q * 256 + lane * 4;
;                         const float4 a0 = *(const float4*)yp, a1 = *(const float4*)(yp + (size_t)TC * D), a2 = *(const float4*)(yp + (size_t)2 * TC * D), a3 = *(const float4*)(yp + (size_t)3 * TC * D);
;                         yv[rr][q] = make_float4(a0.x + a1.x + a2.x + a3.x, a0.y + a1.y + a2.y + a3.y, a0.z + a1.z + a2.z + a3.z, a0.w + a1.w + a2.w + a3.w); }
;                     ss[rr] += yv[rr][q].x * yv[rr][q].x + yv[rr][q].y * yv[rr][q].y + yv[rr][q].z * yv[rr][q].z + yv[rr][q].w * yv[rr][q].w; }
.LBB0_1200:
	s_or_b64 exec, exec, s[22:23]
	s_and_saveexec_b64 s[22:23], s[0:1]
	s_xor_b64 s[22:23], exec, s[22:23]
	s_cbranch_execz .LBB0_1202
	v_add_co_u32_e32 v66, vcc, 0x400000, v36
	s_nop 1
	v_addc_co_u32_e32 v67, vcc, 0, v37, vcc
	v_add_co_u32_e32 v70, vcc, 0x800000, v36
	s_nop 0
	s_nop 0
	s_nop 0
	v_addc_co_u32_e32 v71, vcc, 0, v37, vcc
	v_add_co_u32_e32 v74, vcc, 0xc00000, v36
	s_nop 0
	s_nop 0
	v_addc_co_u32_e32 v75, vcc, 0, v37, vcc
	s_nop 0
	s_waitcnt vmcnt(0) lgkmcnt(0)
	s_waitcnt vmcnt(0)
	v_pk_add_f32 v[62:63], v[208:209], v[212:213]
	v_pk_add_f32 v[64:65], v[210:211], v[214:215]
	s_waitcnt vmcnt(0)
	v_pk_add_f32 v[62:63], v[62:63], v[216:217]
	v_pk_add_f32 v[66:67], v[64:65], v[218:219]
	s_waitcnt vmcnt(0)
	v_pk_add_f32 v[64:65], v[62:63], v[220:221]
	v_pk_add_f32 v[62:63], v[66:67], v[222:223]
	s_andn2_saveexec_b64 s[22:23], s[22:23]
	s_cbranch_execz .LBB0_1204
	s_branch .LBB0_1203

; __device__ __forceinline__ void rowphase(const KQ p_in, int Mupd, const bf16_t* Y, int lu, int gidx, float wgt, const float* gpost,
;                          int Mnext, int ln, const float* gpre, int shidx, int scidx, bf16_t* Hout, bool from_input, int tbeg) {
;     ...
;                     else { const float* yp = (const float*)(p.ws + WS_YP) + (size_t)(t + rr - TL) * D + q * 256 + lane * 4;
;                         const float4 a0 = *(const float4*)yp, a1 = *(const float4*)(yp + (size_t)TC * D), a2 = *(const float4*)(yp + (size_t)2 * TC * D), a3 = *(const float4*)(yp + (size_t)3 * TC * D);
;                         yv[rr][q] = make_float4(a0.x + a1.x + a2.x + a3.x, a0.y + a1.y + a2.y + a3.y, a0.z + a1.z + a2.z + a3.z, a0.w + a1.w + a2.w + a3.w); }
;                     ss[rr] += yv[rr][q].x * yv[rr][q].x + yv[rr][q].y * yv[rr][q].y + yv[rr][q].z * yv[rr][q].z + yv[rr][q].w * yv[rr][q].w; }
.LBB0_1204:
	s_or_b64 exec, exec, s[22:23]
	s_and_saveexec_b64 s[22:23], s[0:1]
	s_xor_b64 s[22:23], exec, s[22:23]
	s_cbranch_execz .LBB0_1206
	v_add_co_u32_e32 v70, vcc, 0x400000, v36
	s_nop 1
	v_addc_co_u32_e32 v71, vcc, 0, v37, vcc
	v_add_co_u32_e32 v74, vcc, 0x800000, v36
	s_nop 0
	s_nop 0
	s_nop 0
	v_addc_co_u32_e32 v75, vcc, 0, v37, vcc
	v_add_co_u32_e32 v78, vcc, 0xc00000, v36
	s_nop 0
	s_nop 0
	v_addc_co_u32_e32 v79, vcc, 0, v37, vcc
	s_nop 0
	s_waitcnt vmcnt(0) lgkmcnt(0)
	s_waitcnt vmcnt(0)
	v_pk_add_f32 v[66:67], v[224:225], v[228:229]
	v_pk_add_f32 v[68:69], v[226:227], v[230:231]
	s_waitcnt vmcnt(0)
	v_pk_add_f32 v[66:67], v[66:67], v[232:233]
	v_pk_add_f32 v[70:71], v[68:69], v[234:235]
	s_waitcnt vmcnt(0)
	v_pk_add_f32 v[68:69], v[66:67], v[236:237]
	v_pk_add_f32 v[66:67], v[70:71], v[238:239]
	s_andn2_saveexec_b64 s[22:23], s[22:23]
	s_cbranch_execz .LBB0_1208
	s_branch .LBB0_1207

; __device__ __forceinline__ void rowphase(const KQ p_in, int Mupd, const bf16_t* Y, int lu, int gidx, float wgt, const float* gpost,
;                          int Mnext, int ln, const float* gpre, int shidx, int scidx, bf16_t* Hout, bool from_input, int tbeg) {
;     ...
;                     else { const float* yp = (const float*)(p.ws + WS_YP) + (size_t)(t + rr - TL) * D + q * 256 + lane * 4;
;                         const float4 a0 = *(const float4*)yp, a1 = *(const float4*)(yp + (size_t)TC * D), a2 = *(const float4*)(yp + (size_t)2 * TC * D), a3 = *(const float4*)(yp + (size_t)3 * TC * D);
;                         yv[rr][q] = make_float4(a0.x + a1.x + a2.x + a3.x, a0.y + a1.y + a2.y + a3.y, a0.z + a1.z + a2.z + a3.z, a0.w + a1.w + a2.w + a3.w); }
;                     ss[rr] += yv[rr][q].x * yv[rr][q].x + yv[rr][q].y * yv[rr][q].y + yv[rr][q].z * yv[rr][q].z + yv[rr][q].w * yv[rr][q].w; }
.LBB0_1208:
	s_or_b64 exec, exec, s[22:23]
	s_and_saveexec_b64 s[22:23], s[0:1]
	s_xor_b64 s[22:23], exec, s[22:23]
	s_cbranch_execz .LBB0_1210
	v_add_co_u32_e32 v38, vcc, 0x400000, v36
	s_nop 1
	v_addc_co_u32_e32 v39, vcc, 0, v37, vcc
	s_nop 0
	s_nop 0
	v_add_co_u32_e32 v38, vcc, 0x800000, v36
	s_waitcnt vmcnt(0) lgkmcnt(0)
	s_waitcnt vmcnt(0)
	v_pk_add_f32 v[70:71], v[240:241], v[244:245]
	v_addc_co_u32_e32 v39, vcc, 0, v37, vcc
	v_add_co_u32_e32 v36, vcc, 0xc00000, v36
	s_nop 0
	s_nop 0
	v_addc_co_u32_e32 v37, vcc, 0, v37, vcc
	s_nop 0
	v_pk_add_f32 v[72:73], v[242:243], v[246:247]
	s_waitcnt lgkmcnt(0)
	s_waitcnt vmcnt(0)
	v_pk_add_f32 v[70:71], v[70:71], v[102:103]
	v_pk_add_f32 v[74:75], v[72:73], v[104:105]
	s_waitcnt vmcnt(0)
	v_pk_add_f32 v[72:73], v[70:71], v[106:107]
	v_pk_add_f32 v[70:71], v[74:75], v[108:109]
	s_andn2_saveexec_b64 s[22:23], s[22:23]
	s_cbranch_execnz .LBB0_1211
	s_branch .LBB0_1212

; __device__ __forceinline__ float bf2f(bf16_t b) { return __uint_as_float(((unsigned)b) << 16); }
; __device__ __forceinline__ void rowphase(const KQ p_in, int Mupd, const bf16_t* Y, int lu, int gidx, float wgt, const float* gpost,
;                          int Mnext, int ln, const float* gpre, int shidx, int scidx, bf16_t* Hout, bool from_input, int tbeg) {
;     ...
;                     if (t < TL) { const bf16x4 yb = *(const bf16x4*)(Y + (size_t)(t + rr) * D + q * 256 + lane * 4);
;                         yv[rr][q] = make_float4(bf2f((bf16_t)yb[0]), bf2f((bf16_t)yb[1]), bf2f((bf16_t)yb[2]), bf2f((bf16_t)yb[3])); }
;                     else { const float* yp = (const float*)(p.ws + WS_YP) + (size_t)(t + rr - TL) * D + q * 256 + lane * 4;
;                         const float4 a0 = *(const float4*)yp, a1 = *(const float4*)(yp + (size_t)TC * D), a2 = *(const float4*)(yp + (size_t)2 * TC * D), a3 = *(const float4*)(yp + (size_t)3 * TC * D);
;                         yv[rr][q] = make_float4(a0.x + a1.x + a2.x + a3.x, a0.y + a1.y + a2.y + a3.y, a0.z + a1.z + a2.z + a3.z, a0.w + a1.w + a2.w + a3.w); }
;                     ss[rr] += yv[rr][q].x * yv[rr][q].x + yv[rr][q].y * yv[rr][q].y + yv[rr][q].z * yv[rr][q].z + yv[rr][q].w * yv[rr][q].w; }
.LBB0_1212:
	s_or_b64 exec, exec, s[22:23]
	v_add_u32_e32 v36, 1, v144
	v_mov_b32_e32 v37, v145
	v_lshlrev_b64 v[36:37], 12, v[36:37]
	v_lshl_add_u64 v[36:37], v[42:43], 0, v[36:37]
	s_and_saveexec_b64 s[22:23], s[0:1]
	s_xor_b64 s[22:23], exec, s[22:23]
	s_cbranch_execz .LBB0_1214
	v_add_co_u32_e32 v38, vcc, 0x400000, v36
	s_nop 1
	v_addc_co_u32_e32 v39, vcc, 0, v37, vcc
	global_load_dwordx4 v[74:77], v[36:37], off
	global_load_dwordx4 v[78:81], v[38:39], off
	v_add_co_u32_e32 v38, vcc, 0x800000, v36
	s_nop 1
	v_addc_co_u32_e32 v39, vcc, 0, v37, vcc
	global_load_dwordx4 v[82:85], v[38:39], off
	v_add_co_u32_e32 v38, vcc, 0xc00000, v36
	s_nop 1
	v_addc_co_u32_e32 v39, vcc, 0, v37, vcc
	global_load_dwordx4 v[86:89], v[38:39], off
	v_add_co_u32_e32 v110, vcc, 0x400000, v36
	s_nop 1
	v_addc_co_u32_e32 v111, vcc, 0, v37, vcc
	v_add_co_u32_e32 v112, vcc, 0x800000, v36
	s_nop 1
	v_addc_co_u32_e32 v113, vcc, 0, v37, vcc
	v_add_co_u32_e32 v114, vcc, 0xc00000, v36
	s_nop 1
	v_addc_co_u32_e32 v115, vcc, 0, v37, vcc
	global_load_dwordx4 v[208:211], v[36:37], off offset:1024
	global_load_dwordx4 v[212:215], v[110:111], off offset:1024
	global_load_dwordx4 v[216:219], v[112:113], off offset:1024
	global_load_dwordx4 v[220:223], v[114:115], off offset:1024
	global_load_dwordx4 v[224:227], v[36:37], off offset:2048
	global_load_dwordx4 v[228:231], v[110:111], off offset:2048
	global_load_dwordx4 v[232:235], v[112:113], off offset:2048
	global_load_dwordx4 v[236:239], v[114:115], off offset:2048
	global_load_dwordx4 v[240:243], v[36:37], off offset:3072
	global_load_dwordx4 v[244:247], v[110:111], off offset:3072
	global_load_dwordx4 v[102:105], v[112:113], off offset:3072
	global_load_dwordx4 v[106:109], v[114:115], off offset:3072
	s_waitcnt vmcnt(16) lgkmcnt(0)
	s_waitcnt vmcnt(14)
	v_pk_add_f32 v[38:39], v[74:75], v[78:79]
	v_pk_add_f32 v[74:75], v[76:77], v[80:81]
	s_waitcnt vmcnt(13)
	v_pk_add_f32 v[38:39], v[38:39], v[82:83]
	v_pk_add_f32 v[74:75], v[74:75], v[84:85]
	s_waitcnt vmcnt(12)
	v_pk_add_f32 v[76:77], v[38:39], v[86:87]
	v_pk_add_f32 v[74:75], v[74:75], v[88:89]

; __device__ __forceinline__ void rowphase(const KQ p_in, int Mupd, const bf16_t* Y, int lu, int gidx, float wgt, const float* gpost,
;                          int Mnext, int ln, const float* gpre, int shidx, int scidx, bf16_t* Hout, bool from_input, int tbeg) {
;     ...
;                     else { const float* yp = (const float*)(p.ws + WS_YP) + (size_t)(t + rr - TL) * D + q * 256 + lane * 4;
;                         const float4 a0 = *(const float4*)yp, a1 = *(const float4*)(yp + (size_t)TC * D), a2 = *(const float4*)(yp + (size_t)2 * TC * D), a3 = *(const float4*)(yp + (size_t)3 * TC * D);
;                         yv[rr][q] = make_float4(a0.x + a1.x + a2.x + a3.x, a0.y + a1.y + a2.y + a3.y, a0.z + a1.z + a2.z + a3.z, a0.w + a1.w + a2.w + a3.w); }
;                     ss[rr] += yv[rr][q].x * yv[rr][q].x + yv[rr][q].y * yv[rr][q].y + yv[rr][q].z * yv[rr][q].z + yv[rr][q].w * yv[rr][q].w; }
.LBB0_1216:
	s_or_b64 exec, exec, s[22:23]
	s_and_saveexec_b64 s[22:23], s[0:1]
	s_xor_b64 s[22:23], exec, s[22:23]
	s_cbranch_execz .LBB0_1218
	v_add_co_u32_e32 v82, vcc, 0x400000, v36
	s_nop 1
	v_addc_co_u32_e32 v83, vcc, 0, v37, vcc
	v_add_co_u32_e32 v86, vcc, 0x800000, v36
	s_nop 0
	s_nop 0
	s_nop 0
	v_addc_co_u32_e32 v87, vcc, 0, v37, vcc
	v_add_co_u32_e32 v90, vcc, 0xc00000, v36
	s_nop 0
	s_nop 0
	v_addc_co_u32_e32 v91, vcc, 0, v37, vcc
	s_nop 0
	s_waitcnt vmcnt(0) lgkmcnt(0)
	s_waitcnt vmcnt(0)
	v_pk_add_f32 v[78:79], v[208:209], v[212:213]
	v_pk_add_f32 v[80:81], v[210:211], v[214:215]
	s_waitcnt vmcnt(0)
	v_pk_add_f32 v[78:79], v[78:79], v[216:217]
	v_pk_add_f32 v[82:83], v[80:81], v[218:219]
	s_waitcnt vmcnt(0)
	v_pk_add_f32 v[80:81], v[78:79], v[220:221]
	v_pk_add_f32 v[78:79], v[82:83], v[222:223]
	s_andn2_saveexec_b64 s[22:23], s[22:23]
	s_cbranch_execz .LBB0_1220
	s_branch .LBB0_1219

; __device__ __forceinline__ void rowphase(const KQ p_in, int Mupd, const bf16_t* Y, int lu, int gidx, float wgt, const float* gpost,
;                          int Mnext, int ln, const float* gpre, int shidx, int scidx, bf16_t* Hout, bool from_input, int tbeg) {
;     ...
;                     else { const float* yp = (const float*)(p.ws + WS_YP) + (size_t)(t + rr - TL) * D + q * 256 + lane * 4;
;                         const float4 a0 = *(const float4*)yp, a1 = *(const float4*)(yp + (size_t)TC * D), a2 = *(const float4*)(yp + (size_t)2 * TC * D), a3 = *(const float4*)(yp + (size_t)3 * TC * D);
;                         yv[rr][q] = make_float4(a0.x + a1.x + a2.x + a3.x, a0.y + a1.y + a2.y + a3.y, a0.z + a1.z + a2.z + a3.z, a0.w + a1.w + a2.w + a3.w); }
;                     ss[rr] += yv[rr][q].x * yv[rr][q].x + yv[rr][q].y * yv[rr][q].y + yv[rr][q].z * yv[rr][q].z + yv[rr][q].w * yv[rr][q].w; }
.LBB0_1220:
	s_or_b64 exec, exec, s[22:23]
	s_and_saveexec_b64 s[22:23], s[0:1]
	s_xor_b64 s[22:23], exec, s[22:23]
	s_cbranch_execz .LBB0_1222
	v_add_co_u32_e32 v86, vcc, 0x400000, v36
	s_nop 1
	v_addc_co_u32_e32 v87, vcc, 0, v37, vcc
	v_add_co_u32_e32 v90, vcc, 0x800000, v36
	s_nop 0
	s_nop 0
	s_nop 0
	v_addc_co_u32_e32 v91, vcc, 0, v37, vcc
	v_add_co_u32_e32 v94, vcc, 0xc00000, v36
	s_nop 0
	s_nop 0
	v_addc_co_u32_e32 v95, vcc, 0, v37, vcc
	s_nop 0
	s_waitcnt vmcnt(0) lgkmcnt(0)
	s_waitcnt vmcnt(0)
	v_pk_add_f32 v[82:83], v[224:225], v[228:229]
	v_pk_add_f32 v[84:85], v[226:227], v[230:231]
	s_waitcnt vmcnt(0)
	v_pk_add_f32 v[82:83], v[82:83], v[232:233]
	v_pk_add_f32 v[84:85], v[84:85], v[234:235]
	s_waitcnt vmcnt(0)
	v_pk_add_f32 v[86:87], v[82:83], v[236:237]
	v_pk_add_f32 v[82:83], v[84:85], v[238:239]
	s_andn2_saveexec_b64 s[22:23], s[22:23]
	s_cbranch_execz .LBB0_1224
	s_branch .LBB0_1223

; __device__ __forceinline__ void rowphase(const KQ p_in, int Mupd, const bf16_t* Y, int lu, int gidx, float wgt, const float* gpost,
;                          int Mnext, int ln, const float* gpre, int shidx, int scidx, bf16_t* Hout, bool from_input, int tbeg) {
;     ...
;                     else { const float* yp = (const float*)(p.ws + WS_YP) + (size_t)(t + rr - TL) * D + q * 256 + lane * 4;
;                         const float4 a0 = *(const float4*)yp, a1 = *(const float4*)(yp + (size_t)TC * D), a2 = *(const float4*)(yp + (size_t)2 * TC * D), a3 = *(const float4*)(yp + (size_t)3 * TC * D);
;                         yv[rr][q] = make_float4(a0.x + a1.x + a2.x + a3.x, a0.y + a1.y + a2.y + a3.y, a0.z + a1.z + a2.z + a3.z, a0.w + a1.w + a2.w + a3.w); }
;                     ss[rr] += yv[rr][q].x * yv[rr][q].x + yv[rr][q].y * yv[rr][q].y + yv[rr][q].z * yv[rr][q].z + yv[rr][q].w * yv[rr][q].w; }
.LBB0_1224:
	s_or_b64 exec, exec, s[22:23]
	s_and_saveexec_b64 s[22:23], s[0:1]
	s_xor_b64 s[0:1], exec, s[22:23]
	s_cbranch_execz .LBB0_1226
	v_add_co_u32_e32 v38, vcc, 0x400000, v36
	s_nop 1
	v_addc_co_u32_e32 v39, vcc, 0, v37, vcc
	s_nop 0
	s_nop 0
	v_add_co_u32_e32 v38, vcc, 0x800000, v36
	s_waitcnt vmcnt(0) lgkmcnt(0)
	s_waitcnt vmcnt(0)
	v_pk_add_f32 v[84:85], v[240:241], v[244:245]
	v_addc_co_u32_e32 v39, vcc, 0, v37, vcc
	v_add_co_u32_e32 v36, vcc, 0xc00000, v36
	s_nop 0
	s_nop 0
	v_addc_co_u32_e32 v37, vcc, 0, v37, vcc
	s_nop 0
	v_pk_add_f32 v[88:89], v[242:243], v[246:247]
	s_waitcnt lgkmcnt(0)
	s_waitcnt vmcnt(0)
	v_pk_add_f32 v[84:85], v[84:85], v[102:103]
	v_pk_add_f32 v[90:91], v[88:89], v[104:105]
	s_waitcnt vmcnt(0)
	v_pk_add_f32 v[88:89], v[84:85], v[106:107]
	v_pk_add_f32 v[84:85], v[90:91], v[108:109]
	s_andn2_saveexec_b64 s[0:1], s[0:1]
	s_cbranch_execnz .LBB0_1227
	s_branch .LBB0_1228

; __device__ __forceinline__ const float* modp(const KQ p, int l, int mr, int idx) { return (const float*)(p.ws + WS_MOD) + ((size_t)(l * 5 + mr) * NMOD + idx) * D; }
; __device__ __forceinline__ void rowphase(const KQ p_in, int Mupd, const bf16_t* Y, int lu, int gidx, float wgt, const float* gpost,
;                          int Mnext, int ln, const float* gpre, int shidx, int scidx, bf16_t* Hout, bool from_input, int tbeg) {
;     ...
;                     ss[rr] += yv[rr][q].x * yv[rr][q].x + yv[rr][q].y * yv[rr][q].y + yv[rr][q].z * yv[rr][q].z + yv[rr][q].w * yv[rr][q].w; }
;             ss[0] = wave_sum(ss[0]); ss[1] = wave_sum(ss[1]);
;             float wgl = wgt; asm volatile("" : "+v"(wgl));
;             const float r0 = rsqrtf(ss[0] * (1.0f / D) + EPS) * wgl, r1 = rsqrtf(ss[1] * (1.0f / D) + EPS) * wgl;
;             const float* gm = modp(p, lu, mr, gidx);
; #pragma unroll
;             for (int q = 0; q < 4; ++q) {
;                 const float4 g4 = *(const float4*)(gm + q * 256 + lane * 4); const float4 p4 = *(const float4*)(gpost + q * 256 + lane * 4);
.LBB0_1228:
	s_or_b64 exec, exec, s[0:1]
	v_mul_f32_e32 v36, v77, v77
	v_pk_fma_f32 v[36:37], v[76:77], v[76:77], v[36:37] op_sel_hi:[1,1,0]
	v_mul_f32_e32 v38, v75, v75
	v_pk_fma_f32 v[36:37], v[74:75], v[74:75], v[36:37]
	v_mul_f32_e32 v90, v79, v79
	v_pk_add_f32 v[36:37], v[38:39], v[36:37] op_sel_hi:[0,1]
	v_mul_f32_e32 v38, v81, v81
	v_pk_fma_f32 v[38:39], v[80:81], v[80:81], v[38:39] op_sel_hi:[1,1,0]
	v_mul_f32_e32 v92, v63, v63
	v_pk_fma_f32 v[38:39], v[78:79], v[78:79], v[38:39]
	v_and_b32_e32 v35, 64, v205
	v_pk_add_f32 v[38:39], v[90:91], v[38:39] op_sel_hi:[0,1]
	v_pk_add_f32 v[36:37], v[36:37], v[38:39]
	v_mul_f32_e32 v38, v87, v87
	v_pk_fma_f32 v[38:39], v[86:87], v[86:87], v[38:39] op_sel_hi:[1,1,0]
	v_mul_f32_e32 v90, v83, v83
	v_pk_fma_f32 v[38:39], v[82:83], v[82:83], v[38:39]
	v_add_u32_e32 v35, 64, v35
	v_pk_add_f32 v[38:39], v[90:91], v[38:39] op_sel_hi:[0,1]
	v_pk_add_f32 v[36:37], v[36:37], v[38:39]
	v_mul_f32_e32 v38, v59, v59
	v_pk_fma_f32 v[38:39], v[58:59], v[58:59], v[38:39] op_sel_hi:[1,1,0]
	v_mul_f32_e32 v90, v61, v61
	v_pk_fma_f32 v[38:39], v[60:61], v[60:61], v[38:39]
	s_mov_b32 s0, 0x3a800000
	v_pk_add_f32 v[38:39], v[90:91], v[38:39] op_sel_hi:[0,1]
	v_mul_f32_e32 v90, v65, v65
	v_pk_fma_f32 v[90:91], v[64:65], v[64:65], v[90:91] op_sel_hi:[1,1,0]
	v_mov_b32_e32 v96, v149
	v_pk_fma_f32 v[90:91], v[62:63], v[62:63], v[90:91]
	s_nop 0
	v_pk_add_f32 v[90:91], v[92:93], v[90:91] op_sel_hi:[0,1]
	v_pk_add_f32 v[38:39], v[38:39], v[90:91]
	v_mul_f32_e32 v90, v69, v69
	v_pk_fma_f32 v[90:91], v[68:69], v[68:69], v[90:91] op_sel_hi:[1,1,0]
	v_mul_f32_e32 v92, v67, v67
	v_pk_fma_f32 v[90:91], v[66:67], v[66:67], v[90:91]
	s_nop 0
	v_pk_add_f32 v[90:91], v[92:93], v[90:91] op_sel_hi:[0,1]
	v_pk_add_f32 v[38:39], v[38:39], v[90:91]
	v_mul_f32_e32 v90, v73, v73
	v_pk_fma_f32 v[90:91], v[72:73], v[72:73], v[90:91] op_sel_hi:[1,1,0]
	v_mul_f32_e32 v92, v71, v71
	v_pk_fma_f32 v[90:91], v[70:71], v[70:71], v[90:91]
	s_nop 0
	v_pk_add_f32 v[90:91], v[92:93], v[90:91] op_sel_hi:[0,1]
	v_pk_add_f32 v[38:39], v[38:39], v[90:91]
	v_mul_f32_e32 v90, v89, v89
	v_pk_fma_f32 v[90:91], v[88:89], v[88:89], v[90:91] op_sel_hi:[1,1,0]
	v_mul_f32_e32 v92, v85, v85
	v_pk_fma_f32 v[90:91], v[84:85], v[84:85], v[90:91]
	v_xor_b32_e32 v39, 16, v205
	v_pk_add_f32 v[90:91], v[92:93], v[90:91] op_sel_hi:[0,1]
	v_pk_add_f32 v[36:37], v[36:37], v[90:91]
	s_nop 0
	v_xor_b32_e32 v37, 32, v205
	v_cmp_lt_i32_e32 vcc, v37, v35
	s_nop 1
	v_cndmask_b32_e32 v37, v205, v37, vcc
	v_cmp_lt_i32_e32 vcc, v39, v35
	v_lshlrev_b32_e32 v37, 2, v37
	ds_bpermute_b32 v91, v37, v38
	v_cndmask_b32_e32 v39, v205, v39, vcc
	v_lshlrev_b32_e32 v57, 2, v39
	v_xor_b32_e32 v39, 8, v205
	v_cmp_lt_i32_e32 vcc, v39, v35
	ds_bpermute_b32 v90, v37, v36
	v_mov_b32_e32 v37, v38
	v_cndmask_b32_e32 v39, v205, v39, vcc
	v_lshlrev_b32_e32 v92, 2, v39
	v_xor_b32_e32 v39, 4, v205
	v_cmp_lt_i32_e32 vcc, v39, v35
	s_waitcnt lgkmcnt(0)
	v_pk_add_f32 v[36:37], v[36:37], v[90:91]
	ds_bpermute_b32 v38, v57, v36
	v_cndmask_b32_e32 v39, v205, v39, vcc
	v_lshlrev_b32_e32 v93, 2, v39
	v_xor_b32_e32 v39, 2, v205
	v_cmp_lt_i32_e32 vcc, v39, v35
	s_nop 1
	v_cndmask_b32_e32 v39, v205, v39, vcc
	v_lshlrev_b32_e32 v94, 2, v39
	v_xor_b32_e32 v39, 1, v205
	v_cmp_lt_i32_e32 vcc, v39, v35
	s_nop 1
	v_cndmask_b32_e32 v35, v205, v39, vcc
	ds_bpermute_b32 v39, v57, v37
	v_lshlrev_b32_e32 v35, 2, v35
	s_waitcnt lgkmcnt(0)
	v_pk_add_f32 v[36:37], v[36:37], v[38:39]
	ds_bpermute_b32 v39, v92, v37
	ds_bpermute_b32 v38, v92, v36
	s_waitcnt lgkmcnt(0)
	v_pk_add_f32 v[36:37], v[36:37], v[38:39]
	ds_bpermute_b32 v39, v93, v37
	ds_bpermute_b32 v38, v93, v36
	s_waitcnt lgkmcnt(0)
	v_pk_add_f32 v[36:37], v[36:37], v[38:39]
	ds_bpermute_b32 v39, v94, v37
	ds_bpermute_b32 v38, v94, v36
	s_waitcnt lgkmcnt(0)
	v_pk_add_f32 v[36:37], v[36:37], v[38:39]
	ds_bpermute_b32 v39, v35, v37
	ds_bpermute_b32 v38, v35, v36
	s_waitcnt lgkmcnt(0)
	v_pk_add_f32 v[36:37], v[36:37], v[38:39]
	s_nop 0
	v_pk_fma_f32 v[36:37], v[36:37], s[0:1], v[146:147] op_sel_hi:[1,0,0]
	s_nop 0
	v_mul_f32_e32 v35, 0x4b800000, v37
	v_cmp_gt_f32_e64 s[0:1], s67, v37
	v_cmp_gt_f32_e32 vcc, s67, v36
	s_nop 0
	v_cndmask_b32_e64 v35, v37, v35, s[0:1]
	v_rsq_f32_e32 v35, v35
	s_nop 0
	v_mul_f32_e32 v37, 0x45800000, v35
	v_cndmask_b32_e64 v100, v35, v37, s[0:1]
	v_mul_f32_e32 v35, 0x4b800000, v36
	v_cndmask_b32_e32 v35, v36, v35, vcc
	v_rsq_f32_e32 v35, v35
	s_mul_i32 s0, s68, 5
	v_mul_f32_e32 v36, 0x45800000, v35
	v_cndmask_b32_e32 v98, v35, v36, vcc
	v_add_u32_e32 v35, s0, v41
	v_lshl_add_u32 v36, v35, 3, v35
	v_ashrrev_i32_e32 v37, 31, v36
	v_lshl_add_u64 v[36:37], v[36:37], 0, s[12:13]
	v_lshlrev_b64 v[36:37], 12, v[36:37]
	v_lshl_add_u64 v[94:95], v[46:47], 0, v[36:37]
	v_mov_b32_e32 v35, v145
	v_lshl_add_u64 v[92:93], v[32:33], 0, v[34:35]
	global_load_dwordx4 v[32:35], v[94:95], off
	global_load_dwordx4 v[36:39], v[48:49], off
	global_load_dwordx4 v[208:211], v[94:95], off offset:1024
	global_load_dwordx4 v[212:215], v[48:49], off offset:1024
	global_load_dwordx4 v[216:219], v[94:95], off offset:2048
	global_load_dwordx4 v[220:223], v[48:49], off offset:2048
	global_load_dwordx4 v[224:227], v[94:95], off offset:3072
	global_load_dwordx4 v[228:231], v[48:49], off offset:3072
	v_lshl_add_u64 v[90:91], v[92:93], 0, s[46:47]
	s_waitcnt vmcnt(8) lgkmcnt(0)
	s_waitcnt vmcnt(7)
	v_mov_b32_e32 v97, v34
	s_waitcnt vmcnt(6)
; __device__ __forceinline__ const float* modp(const KQ p, int l, int mr, int idx) { return (const float*)(p.ws + WS_MOD) + ((size_t)(l * 5 + mr) * NMOD + idx) * D; }
; __device__ __forceinline__ void rowphase(const KQ p_in, int Mupd, const bf16_t* Y, int lu, int gidx, float wgt, const float* gpost,
;                          int Mnext, int ln, const float* gpre, int shidx, int scidx, bf16_t* Hout, bool from_input, int tbeg) {
;     ...
;             for (int q = 0; q < 4; ++q) {
;                 const float4 g4 = *(const float4*)(gm + q * 256 + lane * 4); const float4 p4 = *(const float4*)(gpost + q * 256 + lane * 4);
;                 const float cx = g4.x * p4.x, cy = g4.y * p4.y, cz = g4.z * p4.z, cw = g4.w * p4.w;
;                 xv[0][q].x += r0 * cx * yv[0][q].x; xv[0][q].y += r0 * cy * yv[0][q].y; xv[0][q].z += r0 * cz * yv[0][q].z; xv[0][q].w += r0 * cw * yv[0][q].w;
;                 xv[1][q].x += r1 * cx * yv[1][q].x; xv[1][q].y += r1 * cy * yv[1][q].y; xv[1][q].z += r1 * cz * yv[1][q].z; xv[1][q].w += r1 * cw * yv[1][q].w;
;                 *(float4*)(xr + q * 256 + lane * 4) = xv[0][q]; *(float4*)(xr + D + q * 256 + lane * 4) = xv[1][q];
;             }
;         }
;         if (Hout != nullptr && t < Mnext) {
;             float ss[2] = {0.f, 0.f};
; #pragma unroll
;             for (int rr = 0; rr < 2; ++rr)
; #pragma unroll
;                 for (int q = 0; q < 4; ++q) ss[rr] += xv[rr][q].x * xv[rr][q].x + xv[rr][q].y * xv[rr][q].y + xv[rr][q].z * xv[rr][q].z + xv[rr][q].w * xv[rr][q].w;
;             ss[0] = wave_sum(ss[0]); ss[1] = wave_sum(ss[1]);
;             const float rn[2] = {rsqrtf(ss[0] * (1.0f / D) + EPS), rsqrtf(ss[1] * (1.0f / D) + EPS)};
;             const float* sh = modp(p, ln, mr, shidx); const float* sc = modp(p, ln, mr, scidx);
; #pragma unroll
;             for (int q = 0; q < 4; ++q) {
;                 const float4 g4 = *(const float4*)(gpre + q * 256 + lane * 4); const float4 s4 = *(const float4*)(sc + q * 256 + lane * 4); const float4 h4 = *(const float4*)(sh + q * 256 + lane * 4);
	v_mov_b32_e32 v101, v38
	v_pk_mul_f32 v[100:101], v[96:97], v[100:101]
	v_mov_b32_e32 v97, v35
	v_mov_b32_e32 v99, v39
	v_pk_mul_f32 v[96:97], v[96:97], v[98:99]
	v_pk_mul_f32 v[32:33], v[32:33], v[36:37]
	s_nop 0
	v_pk_mul_f32 v[34:35], v[100:101], v[32:33] op_sel_hi:[0,1]
	v_pk_mul_f32 v[32:33], v[32:33], v[96:97] op_sel_hi:[1,0]
	v_pk_fma_f32 v[24:25], v[58:59], v[34:35], v[24:25]
	v_pk_fma_f32 v[28:29], v[76:77], v[32:33], v[28:29]
	v_mov_b32_e32 v32, v101
	v_mov_b32_e32 v33, v97
	v_pk_mul_f32 v[36:37], v[96:97], v[32:33] op_sel_hi:[0,1]
	v_pk_fma_f32 v[30:31], v[74:75], v[36:37], v[30:31]
	v_add_co_u32_e32 v36, vcc, s42, v92
	v_pk_mul_f32 v[32:33], v[100:101], v[32:33] op_sel_hi:[0,1]
	s_nop 0
	v_addc_co_u32_e32 v37, vcc, 0, v93, vcc
	v_pk_fma_f32 v[26:27], v[60:61], v[32:33], v[26:27]
	global_store_dwordx4 v[36:37], v[28:31], off
	global_store_dwordx4 v[92:93], v[24:27], off
	s_nop 0
	s_nop 0
	s_nop 0
	s_waitcnt lgkmcnt(0)
	s_waitcnt vmcnt(6)
	v_pk_mul_f32 v[32:33], v[208:209], v[212:213]
	s_nop 0
	v_pk_mul_f32 v[36:37], v[100:101], v[32:33] op_sel_hi:[0,1]
	v_pk_mul_f32 v[34:35], v[210:211], v[214:215]
	v_pk_mul_f32 v[32:33], v[96:97], v[32:33] op_sel_hi:[0,1]
	v_pk_fma_f32 v[16:17], v[64:65], v[36:37], v[16:17]
	v_pk_mul_f32 v[36:37], v[100:101], v[34:35] op_sel_hi:[0,1]
	v_pk_fma_f32 v[20:21], v[80:81], v[32:33], v[20:21]
	v_pk_mul_f32 v[32:33], v[96:97], v[34:35] op_sel_hi:[0,1]
	v_pk_fma_f32 v[18:19], v[62:63], v[36:37], v[18:19]
	v_pk_fma_f32 v[22:23], v[78:79], v[32:33], v[22:23]
	global_store_dwordx4 v[92:93], v[16:19], off offset:1024
	global_store_dwordx4 v[90:91], v[20:23], off offset:1024
	s_nop 0
	s_nop 0
	s_waitcnt lgkmcnt(0)
	s_waitcnt vmcnt(6)
	v_pk_mul_f32 v[32:33], v[216:217], v[220:221]
	s_nop 0
	v_pk_mul_f32 v[36:37], v[100:101], v[32:33] op_sel_hi:[0,1]
	v_pk_mul_f32 v[34:35], v[218:219], v[222:223]
	v_pk_mul_f32 v[32:33], v[96:97], v[32:33] op_sel_hi:[0,1]
	v_pk_fma_f32 v[12:13], v[86:87], v[32:33], v[12:13]
	v_pk_mul_f32 v[32:33], v[96:97], v[34:35] op_sel_hi:[0,1]
	v_pk_fma_f32 v[8:9], v[68:69], v[36:37], v[8:9]
	v_pk_mul_f32 v[36:37], v[100:101], v[34:35] op_sel_hi:[0,1]
	v_pk_fma_f32 v[14:15], v[82:83], v[32:33], v[14:15]
	v_pk_fma_f32 v[10:11], v[66:67], v[36:37], v[10:11]
	global_store_dwordx4 v[90:91], v[12:15], off offset:2048
	global_store_dwordx4 v[92:93], v[8:11], off offset:2048
	s_nop 0
	s_nop 0
	s_waitcnt lgkmcnt(0)
	s_waitcnt vmcnt(6)
	v_pk_mul_f32 v[32:33], v[224:225], v[228:229]
	s_nop 0
	v_pk_mul_f32 v[36:37], v[100:101], v[32:33] op_sel_hi:[0,1]
	v_pk_mul_f32 v[34:35], v[226:227], v[230:231]
	v_pk_mul_f32 v[32:33], v[96:97], v[32:33] op_sel_hi:[0,1]
	v_pk_fma_f32 v[0:1], v[72:73], v[36:37], v[0:1]
	v_pk_mul_f32 v[36:37], v[100:101], v[34:35] op_sel_hi:[0,1]
	v_pk_fma_f32 v[4:5], v[88:89], v[32:33], v[4:5]
	v_pk_mul_f32 v[32:33], v[96:97], v[34:35] op_sel_hi:[0,1]
	v_pk_fma_f32 v[2:3], v[70:71], v[36:37], v[2:3]
	v_pk_fma_f32 v[6:7], v[84:85], v[32:33], v[6:7]
	global_store_dwordx4 v[92:93], v[0:3], off offset:3072
	global_store_dwordx4 v[90:91], v[4:7], off offset:3072
.LBB0_1229:
	s_or_b64 exec, exec, s[20:21]
	v_cmp_gt_i32_e32 vcc, s65, v56
	s_and_b64 s[0:1], s[18:19], vcc
	s_and_saveexec_b64 s[20:21], s[0:1]
	s_cbranch_execz .LBB0_1188
	s_waitcnt vmcnt(0) lgkmcnt(0)
	v_mov_b32_e32 v32, v16
	v_mov_b32_e32 v33, v24
	v_mov_b32_e32 v34, v17
	v_mov_b32_e32 v35, v25
	v_pk_mul_f32 v[32:33], v[32:33], v[32:33]
	v_mov_b32_e32 v36, v18
	v_mov_b32_e32 v37, v26
	v_pk_fma_f32 v[32:33], v[34:35], v[34:35], v[32:33]
	v_mov_b32_e32 v38, v19
	v_mov_b32_e32 v39, v27
	v_mov_b32_e32 v56, v0
	v_mov_b32_e32 v57, v8
	v_pk_fma_f32 v[32:33], v[36:37], v[36:37], v[32:33]
	v_mov_b32_e32 v58, v1
	v_mov_b32_e32 v59, v9
	v_pk_fma_f32 v[80:81], v[38:39], v[38:39], v[32:33]
	v_pk_mul_f32 v[32:33], v[56:57], v[56:57]
	v_mov_b32_e32 v60, v2
	v_mov_b32_e32 v61, v10
	v_pk_fma_f32 v[32:33], v[58:59], v[58:59], v[32:33]
	v_mov_b32_e32 v62, v3
	v_mov_b32_e32 v63, v11
	v_mov_b32_e32 v64, v20
	v_mov_b32_e32 v65, v28
	v_pk_fma_f32 v[32:33], v[60:61], v[60:61], v[32:33]
	v_mov_b32_e32 v66, v21
	v_mov_b32_e32 v67, v29
	v_pk_fma_f32 v[60:61], v[62:63], v[62:63], v[32:33]
	v_pk_mul_f32 v[32:33], v[64:65], v[64:65]
	v_mov_b32_e32 v68, v22
	v_mov_b32_e32 v69, v30
	v_pk_fma_f32 v[32:33], v[66:67], v[66:67], v[32:33]
	v_mov_b32_e32 v70, v23
	v_mov_b32_e32 v71, v31
	v_pk_fma_f32 v[32:33], v[68:69], v[68:69], v[32:33]
	v_mov_b32_e32 v72, v4
	v_mov_b32_e32 v73, v12
	v_pk_fma_f32 v[62:63], v[70:71], v[70:71], v[32:33]
	v_add_u32_e32 v32, s24, v41
	v_mov_b32_e32 v74, v5
	v_mov_b32_e32 v75, v13
	v_pk_mul_f32 v[56:57], v[72:73], v[72:73]
	v_lshl_add_u32 v58, v32, 3, v32
	v_mov_b32_e32 v76, v6
	v_mov_b32_e32 v77, v14
	v_ashrrev_i32_e32 v59, 31, v58
	v_pk_fma_f32 v[56:57], v[74:75], v[74:75], v[56:57]
	v_mov_b32_e32 v78, v7
	v_mov_b32_e32 v79, v15
	v_lshl_add_u64 v[32:33], v[58:59], 0, s[16:17]
	v_pk_fma_f32 v[56:57], v[76:77], v[76:77], v[56:57]
	v_lshlrev_b64 v[32:33], 12, v[32:33]
	v_pk_fma_f32 v[66:67], v[78:79], v[78:79], v[56:57]
	v_lshl_add_u64 v[56:57], v[58:59], 0, s[14:15]
	v_lshl_add_u64 v[64:65], v[46:47], 0, v[32:33]
	v_lshlrev_b64 v[56:57], 12, v[56:57]
	global_load_dwordx4 v[32:35], v[64:65], off
	global_load_dwordx4 v[36:39], v[50:51], off
	v_lshl_add_u64 v[68:69], v[46:47], 0, v[56:57]
	global_load_dwordx4 v[56:59], v[68:69], off
	global_load_dwordx4 v[208:211], v[64:65], off offset:1024
	global_load_dwordx4 v[212:215], v[50:51], off offset:1024
	global_load_dwordx4 v[216:219], v[68:69], off offset:1024
	global_load_dwordx4 v[220:223], v[64:65], off offset:2048
	global_load_dwordx4 v[224:227], v[50:51], off offset:2048
	global_load_dwordx4 v[228:231], v[68:69], off offset:2048
	global_load_dwordx4 v[232:235], v[64:65], off offset:3072
	global_load_dwordx4 v[236:239], v[50:51], off offset:3072
	global_load_dwordx4 v[240:243], v[68:69], off offset:3072
	v_and_b32_e32 v41, 64, v205
	v_add_u32_e32 v41, 64, v41
	v_xor_b32_e32 v70, 32, v205
	v_cmp_lt_i32_e32 vcc, v70, v41
	v_mov_b32_e32 v71, v80
	v_mov_b32_e32 v80, v63
	v_cndmask_b32_e32 v70, v205, v70, vcc
	v_lshlrev_b32_e32 v72, 2, v70
	v_mov_b32_e32 v70, v62
	v_pk_add_f32 v[62:63], v[70:71], v[80:81]
	v_mov_b32_e32 v70, v67
	v_mov_b32_e32 v71, v61
	v_pk_add_f32 v[62:63], v[70:71], v[62:63]
	v_mov_b32_e32 v67, v60
	v_pk_add_f32 v[60:61], v[66:67], v[62:63]
	ds_bpermute_b32 v63, v72, v61
	ds_bpermute_b32 v62, v72, v60
	v_xor_b32_e32 v66, 16, v205
	v_cmp_lt_i32_e32 vcc, v66, v41
	s_mov_b32 s0, 0x3a800000
	s_waitcnt lgkmcnt(0)
; __device__ __forceinline__ unsigned cvt_pk_bf16(float lo, float hi) { unsigned r; asm volatile("v_cvt_pk_bf16_f32 %0, %1, %2" : "=v"(r) : "v"(lo), "v"(hi)); return r; }
; __device__ __forceinline__ const float* modp(const KQ p, int l, int mr, int idx) { return (const float*)(p.ws + WS_MOD) + ((size_t)(l * 5 + mr) * NMOD + idx) * D; }
; __device__ __forceinline__ void rowphase(const KQ p_in, int Mupd, const bf16_t* Y, int lu, int gidx, float wgt, const float* gpost,
;                          int Mnext, int ln, const float* gpre, int shidx, int scidx, bf16_t* Hout, bool from_input, int tbeg) {
;     ...
;             ss[0] = wave_sum(ss[0]); ss[1] = wave_sum(ss[1]);
;             const float rn[2] = {rsqrtf(ss[0] * (1.0f / D) + EPS), rsqrtf(ss[1] * (1.0f / D) + EPS)};
;             const float* sh = modp(p, ln, mr, shidx); const float* sc = modp(p, ln, mr, scidx);
; #pragma unroll
;             for (int q = 0; q < 4; ++q) {
;                 const float4 g4 = *(const float4*)(gpre + q * 256 + lane * 4); const float4 s4 = *(const float4*)(sc + q * 256 + lane * 4); const float4 h4 = *(const float4*)(sh + q * 256 + lane * 4);
;                 const float mx_ = g4.x * (1.0f + s4.x), my_ = g4.y * (1.0f + s4.y), mz_ = g4.z * (1.0f + s4.z), mw_ = g4.w * (1.0f + s4.w);
; #pragma unroll
;                 for (int rr = 0; rr < 2; ++rr) {
;                     const float h0 = xv[rr][q].x * rn[rr] * mx_ + h4.x, h1 = xv[rr][q].y * rn[rr] * my_ + h4.y;
;                     const float h2 = xv[rr][q].z * rn[rr] * mz_ + h4.z, h3 = xv[rr][q].w * rn[rr] * mw_ + h4.w;
;                     uint2 pk; pk.x = pg8::cvt_pk_bf16(h0, h1); pk.y = pg8::cvt_pk_bf16(h2, h3);
;                     *(uint2*)(Hout + (size_t)(t + rr) * D + q * 256 + lane * 4) = pk;
;                 }
;             }
;         }
	v_pk_add_f32 v[60:61], v[60:61], v[62:63]
	v_cndmask_b32_e32 v66, v205, v66, vcc
	v_lshlrev_b32_e32 v66, 2, v66
	ds_bpermute_b32 v63, v66, v61
	ds_bpermute_b32 v62, v66, v60
	v_xor_b32_e32 v66, 8, v205
	v_cmp_lt_i32_e32 vcc, v66, v41
	s_waitcnt lgkmcnt(0)
	v_pk_add_f32 v[60:61], v[60:61], v[62:63]
	v_cndmask_b32_e32 v66, v205, v66, vcc
	v_lshlrev_b32_e32 v66, 2, v66
	ds_bpermute_b32 v63, v66, v61
	ds_bpermute_b32 v62, v66, v60
	v_xor_b32_e32 v66, 4, v205
	v_cmp_lt_i32_e32 vcc, v66, v41
	s_waitcnt lgkmcnt(0)
	v_pk_add_f32 v[60:61], v[60:61], v[62:63]
	v_cndmask_b32_e32 v66, v205, v66, vcc
	v_lshlrev_b32_e32 v66, 2, v66
	ds_bpermute_b32 v63, v66, v61
	ds_bpermute_b32 v62, v66, v60
	v_xor_b32_e32 v66, 2, v205
	v_cmp_lt_i32_e32 vcc, v66, v41
	s_waitcnt lgkmcnt(0)
	v_pk_add_f32 v[60:61], v[60:61], v[62:63]
	v_cndmask_b32_e32 v66, v205, v66, vcc
	v_lshlrev_b32_e32 v66, 2, v66
	ds_bpermute_b32 v63, v66, v61
	ds_bpermute_b32 v62, v66, v60
	v_xor_b32_e32 v66, 1, v205
	v_cmp_lt_i32_e32 vcc, v66, v41
	s_waitcnt lgkmcnt(0)
	v_pk_add_f32 v[60:61], v[60:61], v[62:63]
	v_cndmask_b32_e32 v41, v205, v66, vcc
	v_lshlrev_b32_e32 v41, 2, v41
	ds_bpermute_b32 v63, v41, v61
	ds_bpermute_b32 v62, v41, v60
	s_waitcnt lgkmcnt(0)
	v_pk_add_f32 v[60:61], v[60:61], v[62:63]
	s_nop 0
	v_pk_fma_f32 v[60:61], v[60:61], s[0:1], v[146:147] op_sel_hi:[1,0,0]
	s_nop 0
	s_waitcnt vmcnt(11)
	v_add_f32_e32 v32, 1.0, v32
	v_mul_f32_e32 v41, 0x4b800000, v61
	v_cmp_gt_f32_e32 vcc, s67, v61
	v_cmp_gt_f32_e64 s[0:1], s67, v60
	v_add_f32_e32 v33, 1.0, v33
	v_cndmask_b32_e32 v41, v61, v41, vcc
	v_rsq_f32_e32 v41, v41
	v_mul_f32_e32 v61, 0x4b800000, v60
	v_cndmask_b32_e64 v60, v60, v61, s[0:1]
	v_rsq_f32_e32 v60, v60
	v_mul_f32_e32 v61, 0x45800000, v41
	v_cndmask_b32_e32 v41, v41, v61, vcc
	s_waitcnt vmcnt(10)
	v_mul_f32_e32 v32, v36, v32
	v_mul_f32_e32 v33, v37, v33
	v_add_f32_e32 v34, 1.0, v34
	v_add_f32_e32 v35, 1.0, v35
	v_mul_f32_e32 v24, v24, v41
	v_mul_f32_e32 v25, v25, v41
	v_mul_f32_e32 v61, 0x45800000, v60
	v_mul_f32_e32 v34, v38, v34
	v_mul_f32_e32 v35, v39, v35
	s_waitcnt vmcnt(9)
	v_fma_f32 v24, v24, v32, v56
	v_fma_f32 v25, v25, v33, v57
	v_mul_f32_e32 v26, v26, v41
	v_mul_f32_e32 v27, v27, v41
	v_cndmask_b32_e64 v60, v60, v61, s[0:1]
	v_fma_f32 v26, v26, v34, v58
	v_fma_f32 v27, v27, v35, v59
	v_cvt_pk_bf16_f32 v24, v24, v25
	v_cvt_pk_bf16_f32 v25, v26, v27
	v_lshl_add_u64 v[36:37], v[52:53], 0, v[54:55]
	global_store_dwordx2 v[36:37], v[24:25], off
	v_mul_f32_e32 v24, v28, v60
	v_mul_f32_e32 v25, v29, v60
	v_mul_f32_e32 v26, v30, v60
	v_fma_f32 v24, v32, v24, v56
	v_fma_f32 v25, v33, v25, v57
	v_fma_f32 v26, v34, v26, v58
	v_mul_f32_e32 v27, v31, v60
	v_fmac_f32_e32 v59, v35, v27
	v_cvt_pk_bf16_f32 v24, v24, v25
	v_cvt_pk_bf16_f32 v25, v26, v59
	v_add_u32_e32 v26, 0x4001, v144
	v_ashrrev_i32_e32 v27, 31, v26
	v_lshlrev_b64 v[26:27], 11, v[26:27]
	v_lshl_add_u64 v[38:39], v[52:53], 0, v[26:27]
	global_store_dwordx2 v[38:39], v[24:25], off
	s_nop 0
	s_nop 0
	s_nop 0
	s_nop 0
	v_mul_f32_e32 v16, v16, v41
	v_mul_f32_e32 v17, v17, v41
	v_mul_f32_e32 v18, v18, v41
	v_mul_f32_e32 v19, v19, v41
	v_mul_f32_e32 v8, v8, v41
	v_mul_f32_e32 v9, v9, v41
	v_mul_f32_e32 v10, v10, v41
	v_mul_f32_e32 v11, v11, v41
	v_mul_f32_e32 v12, v12, v60
	v_mul_f32_e32 v13, v13, v60
	v_mul_f32_e32 v14, v14, v60
	v_mul_f32_e32 v15, v15, v60
	v_mul_f32_e32 v0, v0, v41
	v_mul_f32_e32 v1, v1, v41
	v_mul_f32_e32 v2, v2, v41
	v_mul_f32_e32 v3, v3, v41
	v_mul_f32_e32 v4, v4, v60
	v_mul_f32_e32 v5, v5, v60
	v_mul_f32_e32 v6, v6, v60
	v_mul_f32_e32 v7, v7, v60
	s_waitcnt lgkmcnt(0)
	s_waitcnt vmcnt(10)
	v_add_f32_e32 v24, 1.0, v208
	v_add_f32_e32 v25, 1.0, v209
	v_add_f32_e32 v26, 1.0, v210
	v_add_f32_e32 v27, 1.0, v211
	s_waitcnt vmcnt(9)
	v_mul_f32_e32 v24, v212, v24
	v_mul_f32_e32 v25, v213, v25
	v_mul_f32_e32 v26, v214, v26
	v_mul_f32_e32 v27, v215, v27
	s_waitcnt vmcnt(8)
	v_fma_f32 v16, v16, v24, v216
	v_fma_f32 v17, v17, v25, v217
	v_fma_f32 v18, v18, v26, v218
	v_fma_f32 v19, v19, v27, v219
	v_cvt_pk_bf16_f32 v16, v16, v17
	v_cvt_pk_bf16_f32 v17, v18, v19
	global_store_dwordx2 v[36:37], v[16:17], off offset:512
	v_mul_f32_e32 v16, v20, v60
	v_mul_f32_e32 v17, v21, v60
	v_fma_f32 v16, v16, v24, v216
	v_fma_f32 v17, v17, v25, v217
	v_mul_f32_e32 v18, v22, v60
	v_mul_f32_e32 v19, v23, v60
	v_fma_f32 v18, v18, v26, v218
	v_fma_f32 v35, v19, v27, v219
	v_cvt_pk_bf16_f32 v16, v16, v17
	v_cvt_pk_bf16_f32 v17, v18, v35
	global_store_dwordx2 v[38:39], v[16:17], off offset:512
	s_nop 0
	s_nop 0
	s_nop 0
	s_nop 0
	s_waitcnt lgkmcnt(0)
	s_waitcnt vmcnt(9)
	v_add_f32_e32 v16, 1.0, v220
	v_add_f32_e32 v17, 1.0, v221
	v_add_f32_e32 v18, 1.0, v222
	v_add_f32_e32 v19, 1.0, v223
	s_waitcnt vmcnt(8)
	v_mul_f32_e32 v16, v224, v16
	v_mul_f32_e32 v17, v225, v17
	v_mul_f32_e32 v18, v226, v18
	v_mul_f32_e32 v19, v227, v19
	s_waitcnt vmcnt(7)
	v_fma_f32 v8, v8, v16, v228
	v_fma_f32 v9, v9, v17, v229
	v_fma_f32 v10, v10, v18, v230
	v_fma_f32 v11, v11, v19, v231
	v_cvt_pk_bf16_f32 v8, v8, v9
	v_cvt_pk_bf16_f32 v9, v10, v11
	v_fma_f32 v12, v12, v16, v228
	v_fma_f32 v13, v13, v17, v229
	v_fma_f32 v14, v14, v18, v230
	v_fma_f32 v27, v15, v19, v231
	global_store_dwordx2 v[36:37], v[8:9], off offset:1024
	v_cvt_pk_bf16_f32 v8, v12, v13
	v_cvt_pk_bf16_f32 v9, v14, v27
	global_store_dwordx2 v[38:39], v[8:9], off offset:1024
	s_nop 0
	s_nop 0
	s_nop 0
	s_nop 0
	s_waitcnt lgkmcnt(0)
	s_waitcnt vmcnt(8)
	v_add_f32_e32 v8, 1.0, v232
	v_add_f32_e32 v9, 1.0, v233
	v_add_f32_e32 v10, 1.0, v234
	v_add_f32_e32 v11, 1.0, v235
	s_waitcnt vmcnt(7)
	v_mul_f32_e32 v8, v236, v8
	v_mul_f32_e32 v9, v237, v9
	v_mul_f32_e32 v10, v238, v10
	v_mul_f32_e32 v11, v239, v11
	s_waitcnt vmcnt(6)
	v_fma_f32 v0, v0, v8, v240
	v_fma_f32 v1, v1, v9, v241
	v_fma_f32 v2, v2, v10, v242
	v_fma_f32 v3, v3, v11, v243
	v_cvt_pk_bf16_f32 v0, v0, v1
	v_cvt_pk_bf16_f32 v1, v2, v3
	v_fma_f32 v4, v4, v8, v240
	v_fma_f32 v5, v5, v9, v241
	v_fma_f32 v6, v6, v10, v242
	v_fma_f32 v19, v7, v11, v243
	global_store_dwordx2 v[36:37], v[0:1], off offset:1536
	v_cvt_pk_bf16_f32 v0, v4, v5
	v_cvt_pk_bf16_f32 v1, v6, v19
	global_store_dwordx2 v[38:39], v[0:1], off offset:1536
	v_mov_b32_e32 v12, v236
	v_mov_b32_e32 v13, v237
	v_mov_b32_e32 v14, v238
	v_mov_b32_e32 v15, v239
	v_mov_b32_e32 v16, v240
	v_mov_b32_e32 v17, v241
	v_mov_b32_e32 v18, v242
	v_mov_b32_e32 v20, v224
	v_mov_b32_e32 v21, v225
	v_mov_b32_e32 v22, v226
	v_mov_b32_e32 v23, v227
	v_mov_b32_e32 v24, v228
	v_mov_b32_e32 v25, v229
	v_mov_b32_e32 v26, v230
	v_mov_b32_e32 v28, v212
	v_mov_b32_e32 v29, v213
	v_mov_b32_e32 v30, v214
	v_mov_b32_e32 v31, v215
	v_mov_b32_e32 v32, v216
	v_mov_b32_e32 v33, v217
	v_mov_b32_e32 v34, v218
	s_branch .LBB0_1188
